# code placement: .p2align 3 in front of the six GEMM K-loop heads (all now 8-byte aligned)
# speedup vs baseline: 1.0047x; 1.0047x over previous
;     __device__ __forceinline__ long arow(int pm) const { return (long)pm * BM; }
;     __device__ __forceinline__ long arow(int pm) const { if (pm < 132) { const int b = pm / 33, i = pm - b * 33; return (long)b * 8192 + 254 * i - 1; } return 32768 + (long)(pm - 132) * 256; }
;     __device__ __forceinline__ bool next(int i, Unit& u) const { if (i > 0) return false; u.pm = pm; u.pn = pn; return true; }
;     __device__ __forceinline__ long arow(int p) const { return (long)p * BM; }
; #define PG8_STAGE(bufoff, gbase, voff) do { _Pragma("unroll") for (int _i = 0; _i < 2; ++_i) \
;         __builtin_amdgcn_global_load_lds((const unsigned*)((const char*)(gbase) + (voff)[_i]), (PG8_LAS unsigned*)(lds + (bufoff) + ldsw + _i * 8192), 16, 0, 0); } while (0)
; #define PG8_LDA(dst, b, h) do { _Pragma("unroll") for (int m = 0; m < 4; ++m) _Pragma("unroll") for (int k = 0; k < 2; ++k) dst[m][k] = *(const PG8_LAS bf16x8*)(lds + PG8_SA(b, h) + aoff + m * 2048 + k * 1024); } while (0)
; template <class Epi, class Sched, bool ALIGN_EPI = false, bool SP2 = false>
; __device__ __forceinline__ void gemm_phase(PG8_LAS unsigned char* lds, const Gemm g, const Sched& S, const Epi& E) {
;     ...
;         const bool has_next = S.next(ui + 1, nxt);
;         const char* nA = has_next ? (const char*)g.A + S.arow(nxt.pm) * rowb : cA; const char* nB = has_next ? (const char*)g.Bt + (size_t)nxt.pn * tstep : cB;
;         for (int t = 0; t < nt; t += 2) {
;             const bool last = (t == nt - 2);
;             const char* a1 = cA + (size_t)(t + 1) * kstep;
;             const char* a2 = last ? nA : cA + (size_t)(t + 2) * kstep; const char* b2 = last ? nB : cB + (size_t)(t + 2) * kstep;
;             const char* a3 = a2 + kstep; const char* b3 = b2 + kstep;
;             if (last && has_next) S.a_ready(nxt);
;             if constexpr (SP2) {
;             PG8_LDB(B0, 0, 0); PG8_LDB(B1, 0, 1); PG8_SCHED; PG8_LDA(At, 0, 0); PG8_STAGE(PG8_SA(1, 1), a1 + hstep, voffA);
;             PG8_WAIT_V(8); PG8_WAIT_L(0); PG8_BAR; PG8_MMA(0, 0, At, B0); PG8_MMA(0, 1, At, B1); PG8_BAR; PG8_SCHED;
;             PG8_LDA(At, 0, 1); PG8_STAGE(PG8_SB(0, 0), b2, voffB); PG8_STAGE(PG8_SB(0, 1), b2 + hstep, voffB); PG8_STAGE(PG8_SA(0, 0), a2, voffA);
;             PG8_WAIT_V(8); PG8_WAIT_L(0); PG8_BAR; PG8_MMA(1, 0, At, B0); PG8_MMA(1, 1, At, B1); PG8_BAR; PG8_SCHED;
.LBB0_184:
	s_ashr_i32 s9, s8, 31
	s_lshl_b64 s[10:11], s[8:9], 19
	s_add_u32 s10, s90, s10
	s_addc_u32 s11, s91, s11
	s_and_b64 s[12:13], s[0:1], exec
	s_cselect_b32 s9, s11, s17
	s_cselect_b32 s36, s10, s16
	s_ashr_i32 s7, s6, 31
	s_lshl_b64 s[12:13], s[6:7], 19
	s_add_u32 s12, s22, s12
	s_addc_u32 s13, s23, s13
	s_and_b64 s[20:21], s[0:1], exec
	s_cselect_b32 s7, s13, s19
	s_cselect_b32 s37, s12, s18
	s_add_u32 s16, s16, 0x40080
	s_addc_u32 s17, s17, 0
	s_add_u32 s38, s18, 0x100
	s_addc_u32 s39, s19, 0
	s_mov_b32 s40, -2
	s_waitcnt vmcnt(0)
	s_add_u32 s18, s16, 0xfffc0080
	s_addc_u32 s19, s17, -1
	s_add_i32 s41, 0, 0x10000
	s_cmp_eq_u32 s40, 12
	s_cselect_b32 s21, s9, s19
	s_cselect_b32 s20, s36, s18
	v_add_u32_e32 v38, s41, v151
	s_cselect_b32 s19, s7, s39
	s_cselect_b32 s18, s37, s38
	s_add_i32 s44, 0, 0x14000
	ds_read_b128 v[146:149], v38
	ds_read_b128 v[154:157], v38 offset:1024
	ds_read_b128 v[158:161], v38 offset:2048
	ds_read_b128 v[162:165], v38 offset:3072
	v_add_u32_e32 v38, s44, v151
	ds_read_b128 v[166:169], v38
	ds_read_b128 v[170:173], v38 offset:1024
	ds_read_b128 v[174:177], v38 offset:2048
	ds_read_b128 v[178:181], v38 offset:3072
	s_add_i32 m0, s25, 0xc000
	ds_read_b128 v[186:189], v153
	ds_read_b128 v[190:193], v153 offset:1024
	ds_read_b128 v[194:197], v153 offset:2048
	ds_read_b128 v[198:201], v153 offset:3072
	ds_read_b128 v[226:229], v153 offset:4096
	ds_read_b128 v[230:233], v153 offset:5120
	ds_read_b128 v[234:237], v153 offset:6144
	ds_read_b128 v[238:241], v153 offset:7168
	global_load_lds_dwordx4 v142, s[16:17]
	s_add_i32 m0, s25, 0xe000
	s_nop 0
	global_load_lds_dwordx4 v144, s[16:17]
	s_waitcnt vmcnt(8)
	s_waitcnt lgkmcnt(0)
	s_barrier
	s_setprio 1
	s_waitcnt lgkmcnt(0)
	v_mfma_f32_16x16x32_bf16 v[134:137], v[146:149], v[186:189], 0
	v_mfma_f32_16x16x32_bf16 v[130:133], v[158:161], v[186:189], 0
	v_mfma_f32_16x16x32_bf16 v[126:129], v[146:149], v[194:197], 0
	v_mfma_f32_16x16x32_bf16 v[118:121], v[158:161], v[194:197], 0
	v_mfma_f32_16x16x32_bf16 v[110:113], v[146:149], v[226:229], 0
	v_mfma_f32_16x16x32_bf16 v[102:105], v[158:161], v[226:229], 0
	v_mfma_f32_16x16x32_bf16 v[94:97], v[146:149], v[234:237], 0
	v_mfma_f32_16x16x32_bf16 v[86:89], v[158:161], v[234:237], 0
	v_mfma_f32_16x16x32_bf16 v[134:137], v[154:157], v[190:193], v[134:137]
	v_mfma_f32_16x16x32_bf16 v[130:133], v[162:165], v[190:193], v[130:133]
	v_mfma_f32_16x16x32_bf16 v[126:129], v[154:157], v[198:201], v[126:129]
	v_mfma_f32_16x16x32_bf16 v[118:121], v[162:165], v[198:201], v[118:121]
	v_mfma_f32_16x16x32_bf16 v[110:113], v[154:157], v[230:233], v[110:113]
	v_mfma_f32_16x16x32_bf16 v[102:105], v[162:165], v[230:233], v[102:105]
	v_mfma_f32_16x16x32_bf16 v[94:97], v[154:157], v[238:241], v[94:97]
	v_mfma_f32_16x16x32_bf16 v[86:89], v[162:165], v[238:241], v[86:89]
	s_setprio 0
	s_setprio 1
	v_mfma_f32_16x16x32_bf16 v[122:125], v[166:169], v[186:189], 0
	v_mfma_f32_16x16x32_bf16 v[114:117], v[174:177], v[186:189], 0
	v_mfma_f32_16x16x32_bf16 v[106:109], v[166:169], v[194:197], 0
	v_mfma_f32_16x16x32_bf16 v[98:101], v[174:177], v[194:197], 0
	v_mfma_f32_16x16x32_bf16 v[90:93], v[166:169], v[226:229], 0
	v_mfma_f32_16x16x32_bf16 v[82:85], v[174:177], v[226:229], 0
	v_mfma_f32_16x16x32_bf16 v[78:81], v[166:169], v[234:237], 0
	v_mfma_f32_16x16x32_bf16 v[74:77], v[174:177], v[234:237], 0
	v_mfma_f32_16x16x32_bf16 v[122:125], v[170:173], v[190:193], v[122:125]
	v_mfma_f32_16x16x32_bf16 v[114:117], v[178:181], v[190:193], v[114:117]
	v_mfma_f32_16x16x32_bf16 v[106:109], v[170:173], v[198:201], v[106:109]
	v_mfma_f32_16x16x32_bf16 v[98:101], v[178:181], v[198:201], v[98:101]
	v_mfma_f32_16x16x32_bf16 v[90:93], v[170:173], v[230:233], v[90:93]
	v_mfma_f32_16x16x32_bf16 v[82:85], v[178:181], v[230:233], v[82:85]
	v_mfma_f32_16x16x32_bf16 v[78:81], v[170:173], v[238:241], v[78:81]
	v_mfma_f32_16x16x32_bf16 v[74:77], v[178:181], v[238:241], v[74:77]
	s_setprio 0
	s_barrier
	s_add_i32 s41, s41, s24
	v_lshl_add_u64 v[202:203], s[18:19], 0, v[34:35]
	s_mov_b32 m0, s41
	ds_read_b128 v[186:189], v153 offset:16384
	ds_read_b128 v[190:193], v153 offset:17408
	ds_read_b128 v[194:197], v153 offset:18432
	ds_read_b128 v[198:201], v153 offset:19456
	ds_read_b128 v[226:229], v153 offset:20480
	ds_read_b128 v[230:233], v153 offset:21504
	ds_read_b128 v[234:237], v153 offset:22528
	ds_read_b128 v[238:241], v153 offset:23552
	global_load_lds_dwordx4 v[202:203], off
	s_add_i32 m0, s41, 0x2000
	s_add_u32 s42, s18, 0x40000
	v_lshl_add_u64 v[208:209], s[18:19], 0, v[36:37]
	s_addc_u32 s43, s19, 0
	s_add_i32 s41, s44, s24
	global_load_lds_dwordx4 v[208:209], off
	s_mov_b32 m0, s41
	v_lshl_add_u64 v[218:219], s[20:21], 0, v[138:139]
	global_load_lds_dwordx4 v34, s[42:43]
	s_add_i32 m0, s41, 0x2000
	s_nop 0
	global_load_lds_dwordx4 v36, s[42:43]
	v_lshl_add_u64 v[210:211], s[20:21], 0, v[140:141]
	s_mov_b32 m0, s25
	s_nop 0
	global_load_lds_dwordx4 v[210:211], off
	s_mov_b32 m0, s26
	s_nop 0
	global_load_lds_dwordx4 v[218:219], off
	s_waitcnt vmcnt(8)
	s_waitcnt lgkmcnt(0)
	s_barrier
; #define PG8_STAGE(bufoff, gbase, voff) do { _Pragma("unroll") for (int _i = 0; _i < 2; ++_i) \
;         __builtin_amdgcn_global_load_lds((const unsigned*)((const char*)(gbase) + (voff)[_i]), (PG8_LAS unsigned*)(lds + (bufoff) + ldsw + _i * 8192), 16, 0, 0); } while (0)
; #define PG8_LDA(dst, b, h) do { _Pragma("unroll") for (int m = 0; m < 4; ++m) _Pragma("unroll") for (int k = 0; k < 2; ++k) dst[m][k] = *(const PG8_LAS bf16x8*)(lds + PG8_SA(b, h) + aoff + m * 2048 + k * 1024); } while (0)
; #define PG8_LDB(dst, b, h) do { _Pragma("unroll") for (int n = 0; n < 2; ++n) _Pragma("unroll") for (int k = 0; k < 2; ++k) dst[n][k] = *(const PG8_LAS bf16x8*)(lds + PG8_SB(b, h) + boff + n * 2048 + k * 1024); } while (0)
; #define PG8_MMA(ai, bj, At, Bt) do { __builtin_amdgcn_s_setprio(1); _Pragma("unroll") for (int m = 0; m < 4; ++m) _Pragma("unroll") for (int n = 0; n < 2; ++n) _Pragma("unroll") for (int k = 0; k < 2; ++k) \
;         acc[ai][bj][m][n] = __builtin_amdgcn_mfma_f32_16x16x32_bf16(Bt[n][k], At[m][k], acc[ai][bj][m][n], 0, 0, 0); __builtin_amdgcn_s_setprio(0); } while (0)
; #define PG8_WAIT_V(n) asm volatile("s_waitcnt vmcnt(" #n ")" ::: "memory")
; #define PG8_WAIT_L(n) asm volatile("s_waitcnt lgkmcnt(" #n ")" ::: "memory")
; #define PG8_BAR __builtin_amdgcn_s_barrier()
; #define PG8_SCHED __builtin_amdgcn_sched_barrier(0)
; template <class Epi, class Sched, bool ALIGN_EPI = false, bool SP2 = false>
; __device__ __forceinline__ void gemm_phase(PG8_LAS unsigned char* lds, const Gemm g, const Sched& S, const Epi& E) {
;     ...
;             PG8_WAIT_V(8); PG8_WAIT_L(0); PG8_BAR; PG8_MMA(1, 0, At, B0); PG8_MMA(1, 1, At, B1); PG8_BAR; PG8_SCHED;
;             PG8_LDB(B0, 1, 0); PG8_LDB(B1, 1, 1); PG8_SCHED; PG8_LDA(At, 1, 0); PG8_STAGE(PG8_SA(0, 1), a2 + hstep, voffA);
;             PG8_WAIT_V(8); PG8_WAIT_L(0); PG8_BAR; PG8_MMA(0, 0, At, B0); PG8_MMA(0, 1, At, B1); PG8_BAR; PG8_SCHED;
	s_setprio 1
	s_waitcnt lgkmcnt(0)
	v_mfma_f32_16x16x32_bf16 v[70:73], v[146:149], v[186:189], 0
	v_mfma_f32_16x16x32_bf16 v[66:69], v[158:161], v[186:189], 0
	v_mfma_f32_16x16x32_bf16 v[62:65], v[146:149], v[194:197], 0
	v_mfma_f32_16x16x32_bf16 v[54:57], v[158:161], v[194:197], 0
	v_mfma_f32_16x16x32_bf16 v[46:49], v[146:149], v[226:229], 0
	v_mfma_f32_16x16x32_bf16 v[30:33], v[158:161], v[226:229], 0
	v_mfma_f32_16x16x32_bf16 v[22:25], v[146:149], v[234:237], 0
	v_mfma_f32_16x16x32_bf16 v[14:17], v[158:161], v[234:237], 0
	v_mfma_f32_16x16x32_bf16 v[70:73], v[154:157], v[190:193], v[70:73]
	v_mfma_f32_16x16x32_bf16 v[66:69], v[162:165], v[190:193], v[66:69]
	v_mfma_f32_16x16x32_bf16 v[62:65], v[154:157], v[198:201], v[62:65]
	v_mfma_f32_16x16x32_bf16 v[54:57], v[162:165], v[198:201], v[54:57]
	v_mfma_f32_16x16x32_bf16 v[46:49], v[154:157], v[230:233], v[46:49]
	v_mfma_f32_16x16x32_bf16 v[30:33], v[162:165], v[230:233], v[30:33]
	v_mfma_f32_16x16x32_bf16 v[22:25], v[154:157], v[238:241], v[22:25]
	v_mfma_f32_16x16x32_bf16 v[14:17], v[162:165], v[238:241], v[14:17]
	s_setprio 0
	s_setprio 1
	v_mfma_f32_16x16x32_bf16 v[58:61], v[166:169], v[186:189], 0
	v_mfma_f32_16x16x32_bf16 v[50:53], v[174:177], v[186:189], 0
	v_mfma_f32_16x16x32_bf16 v[42:45], v[166:169], v[194:197], 0
	v_mfma_f32_16x16x32_bf16 v[26:29], v[174:177], v[194:197], 0
	v_mfma_f32_16x16x32_bf16 v[18:21], v[166:169], v[226:229], 0
	v_mfma_f32_16x16x32_bf16 v[10:13], v[174:177], v[226:229], 0
	v_mfma_f32_16x16x32_bf16 v[6:9], v[166:169], v[234:237], 0
	v_mfma_f32_16x16x32_bf16 v[2:5], v[174:177], v[234:237], 0
	v_mfma_f32_16x16x32_bf16 v[58:61], v[170:173], v[190:193], v[58:61]
	v_mfma_f32_16x16x32_bf16 v[50:53], v[178:181], v[190:193], v[50:53]
	v_mfma_f32_16x16x32_bf16 v[42:45], v[170:173], v[198:201], v[42:45]
	v_mfma_f32_16x16x32_bf16 v[26:29], v[178:181], v[198:201], v[26:29]
	v_mfma_f32_16x16x32_bf16 v[18:21], v[170:173], v[230:233], v[18:21]
	v_mfma_f32_16x16x32_bf16 v[10:13], v[178:181], v[230:233], v[10:13]
	v_mfma_f32_16x16x32_bf16 v[6:9], v[170:173], v[238:241], v[6:9]
	v_mfma_f32_16x16x32_bf16 v[2:5], v[178:181], v[238:241], v[2:5]
	s_setprio 0
	s_barrier
	s_add_i32 s41, 0, 0x18000
	v_add_u32_e32 v38, s41, v151
	s_add_i32 s42, 0, 0x1c000
	ds_read_b128 v[146:149], v38
	ds_read_b128 v[154:157], v38 offset:1024
	ds_read_b128 v[158:161], v38 offset:2048
	ds_read_b128 v[162:165], v38 offset:3072
	v_add_u32_e32 v38, s42, v151
	ds_read_b128 v[166:169], v38
	ds_read_b128 v[170:173], v38 offset:1024
	ds_read_b128 v[174:177], v38 offset:2048
	ds_read_b128 v[178:181], v38 offset:3072
	s_add_u32 s20, s20, 0x40000
	s_addc_u32 s21, s21, 0
	s_mov_b32 m0, s27
	ds_read_b128 v[186:189], v153 offset:32768
	ds_read_b128 v[190:193], v153 offset:33792
	ds_read_b128 v[194:197], v153 offset:34816
	ds_read_b128 v[198:201], v153 offset:35840
	ds_read_b128 v[226:229], v153 offset:36864
	ds_read_b128 v[230:233], v153 offset:37888
	ds_read_b128 v[234:237], v153 offset:38912
	ds_read_b128 v[238:241], v153 offset:39936
	global_load_lds_dwordx4 v140, s[20:21]
	s_mov_b32 m0, s28
	s_nop 0
	global_load_lds_dwordx4 v138, s[20:21]
	s_waitcnt vmcnt(8)
	s_waitcnt lgkmcnt(0)
	s_barrier
	s_setprio 1
	s_waitcnt lgkmcnt(0)
	v_mfma_f32_16x16x32_bf16 v[134:137], v[146:149], v[186:189], v[134:137]
	v_mfma_f32_16x16x32_bf16 v[130:133], v[158:161], v[186:189], v[130:133]
	v_mfma_f32_16x16x32_bf16 v[126:129], v[146:149], v[194:197], v[126:129]
	v_mfma_f32_16x16x32_bf16 v[118:121], v[158:161], v[194:197], v[118:121]
	v_mfma_f32_16x16x32_bf16 v[110:113], v[146:149], v[226:229], v[110:113]
	v_mfma_f32_16x16x32_bf16 v[102:105], v[158:161], v[226:229], v[102:105]
	v_mfma_f32_16x16x32_bf16 v[94:97], v[146:149], v[234:237], v[94:97]
	v_mfma_f32_16x16x32_bf16 v[86:89], v[158:161], v[234:237], v[86:89]
	v_mfma_f32_16x16x32_bf16 v[134:137], v[154:157], v[190:193], v[134:137]
	v_mfma_f32_16x16x32_bf16 v[130:133], v[162:165], v[190:193], v[130:133]
	v_mfma_f32_16x16x32_bf16 v[126:129], v[154:157], v[198:201], v[126:129]
	v_mfma_f32_16x16x32_bf16 v[118:121], v[162:165], v[198:201], v[118:121]
	v_mfma_f32_16x16x32_bf16 v[110:113], v[154:157], v[230:233], v[110:113]
	v_mfma_f32_16x16x32_bf16 v[102:105], v[162:165], v[230:233], v[102:105]
	v_mfma_f32_16x16x32_bf16 v[94:97], v[154:157], v[238:241], v[94:97]
	v_mfma_f32_16x16x32_bf16 v[86:89], v[162:165], v[238:241], v[86:89]
	s_setprio 0
	s_setprio 1
	v_mfma_f32_16x16x32_bf16 v[122:125], v[166:169], v[186:189], v[122:125]
	v_mfma_f32_16x16x32_bf16 v[114:117], v[174:177], v[186:189], v[114:117]
	v_mfma_f32_16x16x32_bf16 v[106:109], v[166:169], v[194:197], v[106:109]
	v_mfma_f32_16x16x32_bf16 v[98:101], v[174:177], v[194:197], v[98:101]
	v_mfma_f32_16x16x32_bf16 v[90:93], v[166:169], v[226:229], v[90:93]
	v_mfma_f32_16x16x32_bf16 v[82:85], v[174:177], v[226:229], v[82:85]
	v_mfma_f32_16x16x32_bf16 v[78:81], v[166:169], v[234:237], v[78:81]
	v_mfma_f32_16x16x32_bf16 v[74:77], v[174:177], v[234:237], v[74:77]
	v_mfma_f32_16x16x32_bf16 v[122:125], v[170:173], v[190:193], v[122:125]
	v_mfma_f32_16x16x32_bf16 v[114:117], v[178:181], v[190:193], v[114:117]
	v_mfma_f32_16x16x32_bf16 v[106:109], v[170:173], v[198:201], v[106:109]
	v_mfma_f32_16x16x32_bf16 v[98:101], v[178:181], v[198:201], v[98:101]
	v_mfma_f32_16x16x32_bf16 v[90:93], v[170:173], v[230:233], v[90:93]
	v_mfma_f32_16x16x32_bf16 v[82:85], v[178:181], v[230:233], v[82:85]
	v_mfma_f32_16x16x32_bf16 v[78:81], v[170:173], v[238:241], v[78:81]
	v_mfma_f32_16x16x32_bf16 v[74:77], v[178:181], v[238:241], v[74:77]
	s_setprio 0
	s_barrier
; #define PG8_STAGE(bufoff, gbase, voff) do { _Pragma("unroll") for (int _i = 0; _i < 2; ++_i) \
;         __builtin_amdgcn_global_load_lds((const unsigned*)((const char*)(gbase) + (voff)[_i]), (PG8_LAS unsigned*)(lds + (bufoff) + ldsw + _i * 8192), 16, 0, 0); } while (0)
; #define PG8_LDA(dst, b, h) do { _Pragma("unroll") for (int m = 0; m < 4; ++m) _Pragma("unroll") for (int k = 0; k < 2; ++k) dst[m][k] = *(const PG8_LAS bf16x8*)(lds + PG8_SA(b, h) + aoff + m * 2048 + k * 1024); } while (0)
; #define PG8_MMA(ai, bj, At, Bt) do { __builtin_amdgcn_s_setprio(1); _Pragma("unroll") for (int m = 0; m < 4; ++m) _Pragma("unroll") for (int n = 0; n < 2; ++n) _Pragma("unroll") for (int k = 0; k < 2; ++k) \
;         acc[ai][bj][m][n] = __builtin_amdgcn_mfma_f32_16x16x32_bf16(Bt[n][k], At[m][k], acc[ai][bj][m][n], 0, 0, 0); __builtin_amdgcn_s_setprio(0); } while (0)
; #define PG8_WAIT_V(n) asm volatile("s_waitcnt vmcnt(" #n ")" ::: "memory")
; #define PG8_WAIT_L(n) asm volatile("s_waitcnt lgkmcnt(" #n ")" ::: "memory")
; #define PG8_BAR __builtin_amdgcn_s_barrier()
; #define PG8_SCHED __builtin_amdgcn_sched_barrier(0)
; template <class Epi, class Sched, bool ALIGN_EPI = false, bool SP2 = false>
; __device__ __forceinline__ void gemm_phase(PG8_LAS unsigned char* lds, const Gemm g, const Sched& S, const Epi& E) {
;     ...
;         for (int t = 0; t < nt; t += 2) {
;             const bool last = (t == nt - 2);
;             const char* a1 = cA + (size_t)(t + 1) * kstep;
;             const char* a2 = last ? nA : cA + (size_t)(t + 2) * kstep; const char* b2 = last ? nB : cB + (size_t)(t + 2) * kstep;
;             const char* a3 = a2 + kstep; const char* b3 = b2 + kstep;
;     ...
;             PG8_LDA(At, 1, 1); PG8_STAGE(PG8_SB(1, 0), b3, voffB); PG8_STAGE(PG8_SB(1, 1), b3 + hstep, voffB); PG8_STAGE(PG8_SA(1, 0), a3, voffA);
;             PG8_WAIT_V(8); PG8_WAIT_L(0); PG8_BAR; PG8_MMA(1, 0, At, B0); PG8_MMA(1, 1, At, B1); PG8_BAR; PG8_SCHED;
	s_add_i32 s20, s41, s24
	v_lshl_add_u64 v[202:203], v[202:203], 0, s[70:71]
	s_mov_b32 m0, s20
	ds_read_b128 v[186:189], v153 offset:49152
	ds_read_b128 v[190:193], v153 offset:50176
	ds_read_b128 v[194:197], v153 offset:51200
	ds_read_b128 v[198:201], v153 offset:52224
	ds_read_b128 v[226:229], v153 offset:53248
	ds_read_b128 v[230:233], v153 offset:54272
	ds_read_b128 v[234:237], v153 offset:55296
	ds_read_b128 v[238:241], v153 offset:56320
	global_load_lds_dwordx4 v[202:203], off
	s_add_i32 m0, s20, 0x2000
	s_add_u32 s18, s18, 0x40080
	v_lshl_add_u64 v[202:203], v[208:209], 0, s[70:71]
	s_addc_u32 s19, s19, 0
	s_add_i32 s20, s42, s24
	global_load_lds_dwordx4 v[202:203], off
	s_mov_b32 m0, s20
	s_nop 0
	global_load_lds_dwordx4 v34, s[18:19]
	s_add_i32 m0, s20, 0x2000
	s_nop 0
	global_load_lds_dwordx4 v36, s[18:19]
	v_lshl_add_u64 v[202:203], v[210:211], 0, s[70:71]
	s_mov_b32 m0, s29
	s_nop 0
	global_load_lds_dwordx4 v[202:203], off
	v_lshl_add_u64 v[202:203], v[218:219], 0, s[70:71]
	s_mov_b32 m0, s30
	s_nop 0
	global_load_lds_dwordx4 v[202:203], off
	s_waitcnt vmcnt(8)
	s_waitcnt lgkmcnt(0)
	s_barrier
	s_setprio 1
	s_waitcnt lgkmcnt(0)
	v_mfma_f32_16x16x32_bf16 v[70:73], v[146:149], v[186:189], v[70:73]
	v_mfma_f32_16x16x32_bf16 v[66:69], v[158:161], v[186:189], v[66:69]
	v_mfma_f32_16x16x32_bf16 v[62:65], v[146:149], v[194:197], v[62:65]
	v_mfma_f32_16x16x32_bf16 v[54:57], v[158:161], v[194:197], v[54:57]
	v_mfma_f32_16x16x32_bf16 v[46:49], v[146:149], v[226:229], v[46:49]
	v_mfma_f32_16x16x32_bf16 v[30:33], v[158:161], v[226:229], v[30:33]
	v_mfma_f32_16x16x32_bf16 v[22:25], v[146:149], v[234:237], v[22:25]
	v_mfma_f32_16x16x32_bf16 v[14:17], v[158:161], v[234:237], v[14:17]
	v_mfma_f32_16x16x32_bf16 v[70:73], v[154:157], v[190:193], v[70:73]
	v_mfma_f32_16x16x32_bf16 v[66:69], v[162:165], v[190:193], v[66:69]
	v_mfma_f32_16x16x32_bf16 v[62:65], v[154:157], v[198:201], v[62:65]
	v_mfma_f32_16x16x32_bf16 v[54:57], v[162:165], v[198:201], v[54:57]
	v_mfma_f32_16x16x32_bf16 v[46:49], v[154:157], v[230:233], v[46:49]
	v_mfma_f32_16x16x32_bf16 v[30:33], v[162:165], v[230:233], v[30:33]
	v_mfma_f32_16x16x32_bf16 v[22:25], v[154:157], v[238:241], v[22:25]
	v_mfma_f32_16x16x32_bf16 v[14:17], v[162:165], v[238:241], v[14:17]
	s_setprio 0
	s_setprio 1
	v_mfma_f32_16x16x32_bf16 v[58:61], v[166:169], v[186:189], v[58:61]
	v_mfma_f32_16x16x32_bf16 v[50:53], v[174:177], v[186:189], v[50:53]
	v_mfma_f32_16x16x32_bf16 v[42:45], v[166:169], v[194:197], v[42:45]
	v_mfma_f32_16x16x32_bf16 v[26:29], v[174:177], v[194:197], v[26:29]
	v_mfma_f32_16x16x32_bf16 v[18:21], v[166:169], v[226:229], v[18:21]
	v_mfma_f32_16x16x32_bf16 v[10:13], v[174:177], v[226:229], v[10:13]
	v_mfma_f32_16x16x32_bf16 v[6:9], v[166:169], v[234:237], v[6:9]
	v_mfma_f32_16x16x32_bf16 v[2:5], v[174:177], v[234:237], v[2:5]
	v_mfma_f32_16x16x32_bf16 v[58:61], v[170:173], v[190:193], v[58:61]
	v_mfma_f32_16x16x32_bf16 v[50:53], v[178:181], v[190:193], v[50:53]
	v_mfma_f32_16x16x32_bf16 v[42:45], v[170:173], v[198:201], v[42:45]
	v_mfma_f32_16x16x32_bf16 v[26:29], v[178:181], v[198:201], v[26:29]
	v_mfma_f32_16x16x32_bf16 v[18:21], v[170:173], v[230:233], v[18:21]
	v_mfma_f32_16x16x32_bf16 v[10:13], v[178:181], v[230:233], v[10:13]
	v_mfma_f32_16x16x32_bf16 v[6:9], v[170:173], v[238:241], v[6:9]
	v_mfma_f32_16x16x32_bf16 v[2:5], v[178:181], v[238:241], v[2:5]
	s_setprio 0
	s_barrier
	s_add_i32 s40, s40, 2
	s_add_u32 s16, s16, 0x100
	s_addc_u32 s17, s17, 0
	s_add_u32 s38, s38, 0x100
	s_addc_u32 s39, s39, 0
	s_cmp_gt_u32 s40, 13
	.p2align 3

;     __device__ __forceinline__ long arow(int pm) const { return (long)pm * BM; }
;     __device__ __forceinline__ long arow(int pm) const { if (pm < 132) { const int b = pm / 33, i = pm - b * 33; return (long)b * 8192 + 254 * i - 1; } return 32768 + (long)(pm - 132) * 256; }
;     __device__ __forceinline__ bool next(int i, Unit& u) const { if (i > 0) return false; u.pm = pm; u.pn = pn; return true; }
;     __device__ __forceinline__ long arow(int p) const { return (long)p * BM; }
; #define PG8_STAGE(bufoff, gbase, voff) do { _Pragma("unroll") for (int _i = 0; _i < 2; ++_i) \
;         __builtin_amdgcn_global_load_lds((const unsigned*)((const char*)(gbase) + (voff)[_i]), (PG8_LAS unsigned*)(lds + (bufoff) + ldsw + _i * 8192), 16, 0, 0); } while (0)
; #define PG8_LDA(dst, b, h) do { _Pragma("unroll") for (int m = 0; m < 4; ++m) _Pragma("unroll") for (int k = 0; k < 2; ++k) dst[m][k] = *(const PG8_LAS bf16x8*)(lds + PG8_SA(b, h) + aoff + m * 2048 + k * 1024); } while (0)
; template <class Epi, class Sched, bool ALIGN_EPI = false, bool SP2 = false>
; __device__ __forceinline__ void gemm_phase(PG8_LAS unsigned char* lds, const Gemm g, const Sched& S, const Epi& E) {
;     ...
;         const bool has_next = S.next(ui + 1, nxt);
;         const char* nA = has_next ? (const char*)g.A + S.arow(nxt.pm) * rowb : cA; const char* nB = has_next ? (const char*)g.Bt + (size_t)nxt.pn * tstep : cB;
;         for (int t = 0; t < nt; t += 2) {
;             const bool last = (t == nt - 2);
;             const char* a1 = cA + (size_t)(t + 1) * kstep;
;             const char* a2 = last ? nA : cA + (size_t)(t + 2) * kstep; const char* b2 = last ? nB : cB + (size_t)(t + 2) * kstep;
;             const char* a3 = a2 + kstep; const char* b3 = b2 + kstep;
;             if (last && has_next) S.a_ready(nxt);
;             if constexpr (SP2) {
;             PG8_LDB(B0, 0, 0); PG8_LDB(B1, 0, 1); PG8_SCHED; PG8_LDA(At, 0, 0); PG8_STAGE(PG8_SA(1, 1), a1 + hstep, voffA);
;             PG8_WAIT_V(8); PG8_WAIT_L(0); PG8_BAR; PG8_MMA(0, 0, At, B0); PG8_MMA(0, 1, At, B1); PG8_BAR; PG8_SCHED;
;             PG8_LDA(At, 0, 1); PG8_STAGE(PG8_SB(0, 0), b2, voffB); PG8_STAGE(PG8_SB(0, 1), b2 + hstep, voffB); PG8_STAGE(PG8_SA(0, 0), a2, voffA);
;             PG8_WAIT_V(8); PG8_WAIT_L(0); PG8_BAR; PG8_MMA(1, 0, At, B0); PG8_MMA(1, 1, At, B1); PG8_BAR; PG8_SCHED;
.LBB0_541:
	s_ashr_i32 s9, s8, 31
	s_lshl_b64 s[10:11], s[8:9], 19
	s_add_u32 s10, s81, s10
	s_addc_u32 s11, s85, s11
	s_and_b64 s[12:13], s[4:5], exec
	s_cselect_b32 s9, s11, s17
	s_cselect_b32 s15, s10, s16
	s_ashr_i32 s7, s6, 31
	s_lshl_b64 s[12:13], s[6:7], 19
	s_add_u32 s12, s26, s12
	s_addc_u32 s13, s27, s13
	s_and_b64 s[20:21], s[4:5], exec
	s_cselect_b32 s7, s13, s19
	s_cselect_b32 s41, s12, s18
	s_add_u32 s42, s18, 0x100
	s_addc_u32 s43, s19, 0
	s_mov_b32 s44, -2
	s_add_u32 s18, s16, 0x100
	s_addc_u32 s19, s17, 0
	s_add_i32 s45, 0, 0x10000
	s_cmp_eq_u32 s44, 12
	s_cselect_b32 s23, s9, s19
	s_cselect_b32 s22, s15, s18
	v_add_u32_e32 v38, s45, v168
	s_cselect_b32 s21, s7, s43
	s_cselect_b32 s20, s41, s42
	s_add_i32 s46, 0, 0x14000
	ds_read_b128 v[138:141], v38
	ds_read_b128 v[162:165], v38 offset:1024
	ds_read_b128 v[172:175], v38 offset:2048
	ds_read_b128 v[176:179], v38 offset:3072
	v_add_u32_e32 v38, s46, v168
	ds_read_b128 v[186:189], v38
	ds_read_b128 v[190:193], v38 offset:1024
	ds_read_b128 v[194:197], v38 offset:2048
	ds_read_b128 v[198:201], v38 offset:3072
	v_lshl_add_u64 v[166:167], s[16:17], 0, v[158:159]
	s_add_i32 m0, s29, 0xc000
	ds_read_b128 v[226:229], v170
	ds_read_b128 v[230:233], v170 offset:1024
	ds_read_b128 v[234:237], v170 offset:2048
	ds_read_b128 v[238:241], v170 offset:3072
	ds_read_b128 v[242:245], v170 offset:4096
	ds_read_b128 v[246:249], v170 offset:5120
	ds_read_b128 v[218:221], v170 offset:6144
	ds_read_b128 v[208:211], v170 offset:7168
	global_load_lds_dwordx4 v[166:167], off
	v_lshl_add_u64 v[166:167], s[16:17], 0, v[160:161]
	s_add_i32 m0, s29, 0xe000
	s_nop 0
	global_load_lds_dwordx4 v[166:167], off
	s_waitcnt vmcnt(8)
	s_waitcnt lgkmcnt(0)
	s_barrier
	s_setprio 1
	s_waitcnt lgkmcnt(0)
	v_mfma_f32_16x16x32_bf16 v[134:137], v[138:141], v[226:229], 0
	v_mfma_f32_16x16x32_bf16 v[106:109], v[172:175], v[226:229], 0
	v_mfma_f32_16x16x32_bf16 v[130:133], v[138:141], v[234:237], 0
	v_mfma_f32_16x16x32_bf16 v[102:105], v[172:175], v[234:237], 0
	v_mfma_f32_16x16x32_bf16 v[126:129], v[138:141], v[242:245], 0
	v_mfma_f32_16x16x32_bf16 v[98:101], v[172:175], v[242:245], 0
	v_mfma_f32_16x16x32_bf16 v[122:125], v[138:141], v[218:221], 0
	v_mfma_f32_16x16x32_bf16 v[90:93], v[172:175], v[218:221], 0
	v_mfma_f32_16x16x32_bf16 v[134:137], v[162:165], v[230:233], v[134:137]
	v_mfma_f32_16x16x32_bf16 v[106:109], v[176:179], v[230:233], v[106:109]
	v_mfma_f32_16x16x32_bf16 v[130:133], v[162:165], v[238:241], v[130:133]
	v_mfma_f32_16x16x32_bf16 v[102:105], v[176:179], v[238:241], v[102:105]
	v_mfma_f32_16x16x32_bf16 v[126:129], v[162:165], v[246:249], v[126:129]
	v_mfma_f32_16x16x32_bf16 v[98:101], v[176:179], v[246:249], v[98:101]
	v_mfma_f32_16x16x32_bf16 v[122:125], v[162:165], v[208:211], v[122:125]
	v_mfma_f32_16x16x32_bf16 v[90:93], v[176:179], v[208:211], v[90:93]
	s_setprio 0
	s_setprio 1
	v_mfma_f32_16x16x32_bf16 v[82:85], v[186:189], v[226:229], 0
	v_mfma_f32_16x16x32_bf16 v[54:57], v[194:197], v[226:229], 0
	v_mfma_f32_16x16x32_bf16 v[74:77], v[186:189], v[234:237], 0
	v_mfma_f32_16x16x32_bf16 v[46:49], v[194:197], v[234:237], 0
	v_mfma_f32_16x16x32_bf16 v[66:69], v[186:189], v[242:245], 0
	v_mfma_f32_16x16x32_bf16 v[30:33], v[194:197], v[242:245], 0
	v_mfma_f32_16x16x32_bf16 v[58:61], v[186:189], v[218:221], 0
	v_mfma_f32_16x16x32_bf16 v[22:25], v[194:197], v[218:221], 0
	v_mfma_f32_16x16x32_bf16 v[82:85], v[190:193], v[230:233], v[82:85]
	v_mfma_f32_16x16x32_bf16 v[54:57], v[198:201], v[230:233], v[54:57]
	v_mfma_f32_16x16x32_bf16 v[74:77], v[190:193], v[238:241], v[74:77]
	v_mfma_f32_16x16x32_bf16 v[46:49], v[198:201], v[238:241], v[46:49]
	v_mfma_f32_16x16x32_bf16 v[66:69], v[190:193], v[246:249], v[66:69]
	v_mfma_f32_16x16x32_bf16 v[30:33], v[198:201], v[246:249], v[30:33]
	v_mfma_f32_16x16x32_bf16 v[58:61], v[190:193], v[208:211], v[58:61]
	v_mfma_f32_16x16x32_bf16 v[22:25], v[198:201], v[208:211], v[22:25]
	s_setprio 0
	s_barrier
	s_add_i32 s16, s45, s28
	v_lshl_add_u64 v[166:167], s[20:21], 0, v[34:35]
	s_mov_b32 m0, s16
	ds_read_b128 v[208:211], v170 offset:16384
	ds_read_b128 v[218:221], v170 offset:17408
	ds_read_b128 v[226:229], v170 offset:18432
	ds_read_b128 v[230:233], v170 offset:19456
	ds_read_b128 v[234:237], v170 offset:20480
	ds_read_b128 v[238:241], v170 offset:21504
	ds_read_b128 v[242:245], v170 offset:22528
	ds_read_b128 v[246:249], v170 offset:23552
	global_load_lds_dwordx4 v[166:167], off
	s_add_i32 m0, s16, 0x2000
	s_add_u32 s16, s20, 0x40000
	v_lshl_add_u64 v[180:181], s[20:21], 0, v[36:37]
	s_addc_u32 s17, s21, 0
	s_add_i32 s45, s46, s28
	global_load_lds_dwordx4 v[180:181], off
	v_lshl_add_u64 v[202:203], s[16:17], 0, v[34:35]
	s_mov_b32 m0, s45
	v_lshl_add_u64 v[250:251], s[22:23], 0, v[36:37]
	global_load_lds_dwordx4 v[202:203], off
	v_lshl_add_u64 v[202:203], s[16:17], 0, v[36:37]
	s_add_i32 m0, s45, 0x2000
	s_nop 0
	global_load_lds_dwordx4 v[202:203], off
	v_lshl_add_u64 v[202:203], s[22:23], 0, v[34:35]
	s_mov_b32 m0, s29
	s_nop 0
	global_load_lds_dwordx4 v[202:203], off
	s_mov_b32 m0, s30
	s_nop 0
	global_load_lds_dwordx4 v[250:251], off
	s_waitcnt vmcnt(8)
	s_waitcnt lgkmcnt(0)
	s_barrier
; #define PG8_STAGE(bufoff, gbase, voff) do { _Pragma("unroll") for (int _i = 0; _i < 2; ++_i) \
;         __builtin_amdgcn_global_load_lds((const unsigned*)((const char*)(gbase) + (voff)[_i]), (PG8_LAS unsigned*)(lds + (bufoff) + ldsw + _i * 8192), 16, 0, 0); } while (0)
; #define PG8_LDA(dst, b, h) do { _Pragma("unroll") for (int m = 0; m < 4; ++m) _Pragma("unroll") for (int k = 0; k < 2; ++k) dst[m][k] = *(const PG8_LAS bf16x8*)(lds + PG8_SA(b, h) + aoff + m * 2048 + k * 1024); } while (0)
; #define PG8_LDB(dst, b, h) do { _Pragma("unroll") for (int n = 0; n < 2; ++n) _Pragma("unroll") for (int k = 0; k < 2; ++k) dst[n][k] = *(const PG8_LAS bf16x8*)(lds + PG8_SB(b, h) + boff + n * 2048 + k * 1024); } while (0)
; #define PG8_MMA(ai, bj, At, Bt) do { __builtin_amdgcn_s_setprio(1); _Pragma("unroll") for (int m = 0; m < 4; ++m) _Pragma("unroll") for (int n = 0; n < 2; ++n) _Pragma("unroll") for (int k = 0; k < 2; ++k) \
;         acc[ai][bj][m][n] = __builtin_amdgcn_mfma_f32_16x16x32_bf16(Bt[n][k], At[m][k], acc[ai][bj][m][n], 0, 0, 0); __builtin_amdgcn_s_setprio(0); } while (0)
; #define PG8_WAIT_V(n) asm volatile("s_waitcnt vmcnt(" #n ")" ::: "memory")
; #define PG8_WAIT_L(n) asm volatile("s_waitcnt lgkmcnt(" #n ")" ::: "memory")
; #define PG8_BAR __builtin_amdgcn_s_barrier()
; #define PG8_SCHED __builtin_amdgcn_sched_barrier(0)
; template <class Epi, class Sched, bool ALIGN_EPI = false, bool SP2 = false>
; __device__ __forceinline__ void gemm_phase(PG8_LAS unsigned char* lds, const Gemm g, const Sched& S, const Epi& E) {
;     ...
;             PG8_WAIT_V(8); PG8_WAIT_L(0); PG8_BAR; PG8_MMA(1, 0, At, B0); PG8_MMA(1, 1, At, B1); PG8_BAR; PG8_SCHED;
;             PG8_LDB(B0, 1, 0); PG8_LDB(B1, 1, 1); PG8_SCHED; PG8_LDA(At, 1, 0); PG8_STAGE(PG8_SA(0, 1), a2 + hstep, voffA);
;             PG8_WAIT_V(8); PG8_WAIT_L(0); PG8_BAR; PG8_MMA(0, 0, At, B0); PG8_MMA(0, 1, At, B1); PG8_BAR; PG8_SCHED;
	s_setprio 1
	s_waitcnt lgkmcnt(0)
	v_mfma_f32_16x16x32_bf16 v[118:121], v[138:141], v[208:211], 0
	v_mfma_f32_16x16x32_bf16 v[86:89], v[172:175], v[208:211], 0
	v_mfma_f32_16x16x32_bf16 v[114:117], v[138:141], v[226:229], 0
	v_mfma_f32_16x16x32_bf16 v[78:81], v[172:175], v[226:229], 0
	v_mfma_f32_16x16x32_bf16 v[110:113], v[138:141], v[234:237], 0
	v_mfma_f32_16x16x32_bf16 v[70:73], v[172:175], v[234:237], 0
	v_mfma_f32_16x16x32_bf16 v[94:97], v[138:141], v[242:245], 0
	v_mfma_f32_16x16x32_bf16 v[62:65], v[172:175], v[242:245], 0
	v_mfma_f32_16x16x32_bf16 v[118:121], v[162:165], v[218:221], v[118:121]
	v_mfma_f32_16x16x32_bf16 v[86:89], v[176:179], v[218:221], v[86:89]
	v_mfma_f32_16x16x32_bf16 v[114:117], v[162:165], v[230:233], v[114:117]
	v_mfma_f32_16x16x32_bf16 v[78:81], v[176:179], v[230:233], v[78:81]
	v_mfma_f32_16x16x32_bf16 v[110:113], v[162:165], v[238:241], v[110:113]
	v_mfma_f32_16x16x32_bf16 v[70:73], v[176:179], v[238:241], v[70:73]
	v_mfma_f32_16x16x32_bf16 v[94:97], v[162:165], v[246:249], v[94:97]
	v_mfma_f32_16x16x32_bf16 v[62:65], v[176:179], v[246:249], v[62:65]
	s_setprio 0
	s_setprio 1
	v_mfma_f32_16x16x32_bf16 v[50:53], v[186:189], v[208:211], 0
	v_mfma_f32_16x16x32_bf16 v[14:17], v[194:197], v[208:211], 0
	v_mfma_f32_16x16x32_bf16 v[42:45], v[186:189], v[226:229], 0
	v_mfma_f32_16x16x32_bf16 v[10:13], v[194:197], v[226:229], 0
	v_mfma_f32_16x16x32_bf16 v[26:29], v[186:189], v[234:237], 0
	v_mfma_f32_16x16x32_bf16 v[6:9], v[194:197], v[234:237], 0
	v_mfma_f32_16x16x32_bf16 v[18:21], v[186:189], v[242:245], 0
	v_mfma_f32_16x16x32_bf16 v[2:5], v[194:197], v[242:245], 0
	v_mfma_f32_16x16x32_bf16 v[50:53], v[190:193], v[218:221], v[50:53]
	v_mfma_f32_16x16x32_bf16 v[14:17], v[198:201], v[218:221], v[14:17]
	v_mfma_f32_16x16x32_bf16 v[42:45], v[190:193], v[230:233], v[42:45]
	v_mfma_f32_16x16x32_bf16 v[10:13], v[198:201], v[230:233], v[10:13]
	v_mfma_f32_16x16x32_bf16 v[26:29], v[190:193], v[238:241], v[26:29]
	v_mfma_f32_16x16x32_bf16 v[6:9], v[198:201], v[238:241], v[6:9]
	v_mfma_f32_16x16x32_bf16 v[18:21], v[190:193], v[246:249], v[18:21]
	v_mfma_f32_16x16x32_bf16 v[2:5], v[198:201], v[246:249], v[2:5]
	s_setprio 0
	s_barrier
	s_add_i32 s45, 0, 0x18000
	v_add_u32_e32 v38, s45, v168
	s_add_i32 s46, 0, 0x1c000
	ds_read_b128 v[138:141], v38
	ds_read_b128 v[162:165], v38 offset:1024
	ds_read_b128 v[172:175], v38 offset:2048
	ds_read_b128 v[176:179], v38 offset:3072
	v_add_u32_e32 v38, s46, v168
	ds_read_b128 v[186:189], v38
	ds_read_b128 v[190:193], v38 offset:1024
	ds_read_b128 v[194:197], v38 offset:2048
	ds_read_b128 v[198:201], v38 offset:3072
	s_add_u32 s16, s22, 0x40000
	s_addc_u32 s17, s23, 0
	s_mov_b32 m0, s31
	v_lshl_add_u64 v[212:213], s[16:17], 0, v[34:35]
	ds_read_b128 v[208:211], v170 offset:32768
	ds_read_b128 v[218:221], v170 offset:33792
	ds_read_b128 v[226:229], v170 offset:34816
	ds_read_b128 v[230:233], v170 offset:35840
	ds_read_b128 v[234:237], v170 offset:36864
	ds_read_b128 v[238:241], v170 offset:37888
	ds_read_b128 v[242:245], v170 offset:38912
	ds_read_b128 v[246:249], v170 offset:39936
	global_load_lds_dwordx4 v[212:213], off
	v_lshl_add_u64 v[212:213], s[16:17], 0, v[36:37]
	s_mov_b32 m0, s34
	s_nop 0
	global_load_lds_dwordx4 v[212:213], off
	s_waitcnt vmcnt(8)
	s_waitcnt lgkmcnt(0)
	s_barrier
	s_setprio 1
	s_waitcnt lgkmcnt(0)
	v_mfma_f32_16x16x32_bf16 v[134:137], v[138:141], v[208:211], v[134:137]
	v_mfma_f32_16x16x32_bf16 v[106:109], v[172:175], v[208:211], v[106:109]
	v_mfma_f32_16x16x32_bf16 v[130:133], v[138:141], v[226:229], v[130:133]
	v_mfma_f32_16x16x32_bf16 v[102:105], v[172:175], v[226:229], v[102:105]
	v_mfma_f32_16x16x32_bf16 v[126:129], v[138:141], v[234:237], v[126:129]
	v_mfma_f32_16x16x32_bf16 v[98:101], v[172:175], v[234:237], v[98:101]
	v_mfma_f32_16x16x32_bf16 v[122:125], v[138:141], v[242:245], v[122:125]
	v_mfma_f32_16x16x32_bf16 v[90:93], v[172:175], v[242:245], v[90:93]
	v_mfma_f32_16x16x32_bf16 v[134:137], v[162:165], v[218:221], v[134:137]
	v_mfma_f32_16x16x32_bf16 v[106:109], v[176:179], v[218:221], v[106:109]
	v_mfma_f32_16x16x32_bf16 v[130:133], v[162:165], v[230:233], v[130:133]
	v_mfma_f32_16x16x32_bf16 v[102:105], v[176:179], v[230:233], v[102:105]
	v_mfma_f32_16x16x32_bf16 v[126:129], v[162:165], v[238:241], v[126:129]
	v_mfma_f32_16x16x32_bf16 v[98:101], v[176:179], v[238:241], v[98:101]
	v_mfma_f32_16x16x32_bf16 v[122:125], v[162:165], v[246:249], v[122:125]
	v_mfma_f32_16x16x32_bf16 v[90:93], v[176:179], v[246:249], v[90:93]
	s_setprio 0
	s_setprio 1
	v_mfma_f32_16x16x32_bf16 v[82:85], v[186:189], v[208:211], v[82:85]
	v_mfma_f32_16x16x32_bf16 v[54:57], v[194:197], v[208:211], v[54:57]
	v_mfma_f32_16x16x32_bf16 v[74:77], v[186:189], v[226:229], v[74:77]
	v_mfma_f32_16x16x32_bf16 v[46:49], v[194:197], v[226:229], v[46:49]
	v_mfma_f32_16x16x32_bf16 v[66:69], v[186:189], v[234:237], v[66:69]
	v_mfma_f32_16x16x32_bf16 v[30:33], v[194:197], v[234:237], v[30:33]
	v_mfma_f32_16x16x32_bf16 v[58:61], v[186:189], v[242:245], v[58:61]
	v_mfma_f32_16x16x32_bf16 v[22:25], v[194:197], v[242:245], v[22:25]
	v_mfma_f32_16x16x32_bf16 v[82:85], v[190:193], v[218:221], v[82:85]
	v_mfma_f32_16x16x32_bf16 v[54:57], v[198:201], v[218:221], v[54:57]
	v_mfma_f32_16x16x32_bf16 v[74:77], v[190:193], v[230:233], v[74:77]
	v_mfma_f32_16x16x32_bf16 v[46:49], v[198:201], v[230:233], v[46:49]
	v_mfma_f32_16x16x32_bf16 v[66:69], v[190:193], v[238:241], v[66:69]
	v_mfma_f32_16x16x32_bf16 v[30:33], v[198:201], v[238:241], v[30:33]
	v_mfma_f32_16x16x32_bf16 v[58:61], v[190:193], v[246:249], v[58:61]
	v_mfma_f32_16x16x32_bf16 v[22:25], v[198:201], v[246:249], v[22:25]
	s_setprio 0
	s_barrier
; #define PG8_STAGE(bufoff, gbase, voff) do { _Pragma("unroll") for (int _i = 0; _i < 2; ++_i) \
;         __builtin_amdgcn_global_load_lds((const unsigned*)((const char*)(gbase) + (voff)[_i]), (PG8_LAS unsigned*)(lds + (bufoff) + ldsw + _i * 8192), 16, 0, 0); } while (0)
; #define PG8_LDA(dst, b, h) do { _Pragma("unroll") for (int m = 0; m < 4; ++m) _Pragma("unroll") for (int k = 0; k < 2; ++k) dst[m][k] = *(const PG8_LAS bf16x8*)(lds + PG8_SA(b, h) + aoff + m * 2048 + k * 1024); } while (0)
; #define PG8_MMA(ai, bj, At, Bt) do { __builtin_amdgcn_s_setprio(1); _Pragma("unroll") for (int m = 0; m < 4; ++m) _Pragma("unroll") for (int n = 0; n < 2; ++n) _Pragma("unroll") for (int k = 0; k < 2; ++k) \
;         acc[ai][bj][m][n] = __builtin_amdgcn_mfma_f32_16x16x32_bf16(Bt[n][k], At[m][k], acc[ai][bj][m][n], 0, 0, 0); __builtin_amdgcn_s_setprio(0); } while (0)
; #define PG8_WAIT_V(n) asm volatile("s_waitcnt vmcnt(" #n ")" ::: "memory")
; #define PG8_WAIT_L(n) asm volatile("s_waitcnt lgkmcnt(" #n ")" ::: "memory")
; #define PG8_BAR __builtin_amdgcn_s_barrier()
; #define PG8_SCHED __builtin_amdgcn_sched_barrier(0)
; template <class Epi, class Sched, bool ALIGN_EPI = false, bool SP2 = false>
; __device__ __forceinline__ void gemm_phase(PG8_LAS unsigned char* lds, const Gemm g, const Sched& S, const Epi& E) {
;     ...
;         for (int t = 0; t < nt; t += 2) {
;             const bool last = (t == nt - 2);
;             const char* a1 = cA + (size_t)(t + 1) * kstep;
;             const char* a2 = last ? nA : cA + (size_t)(t + 2) * kstep; const char* b2 = last ? nB : cB + (size_t)(t + 2) * kstep;
;             const char* a3 = a2 + kstep; const char* b3 = b2 + kstep;
;     ...
;             PG8_LDA(At, 1, 1); PG8_STAGE(PG8_SB(1, 0), b3, voffB); PG8_STAGE(PG8_SB(1, 1), b3 + hstep, voffB); PG8_STAGE(PG8_SA(1, 0), a3, voffA);
;             PG8_WAIT_V(8); PG8_WAIT_L(0); PG8_BAR; PG8_MMA(1, 0, At, B0); PG8_MMA(1, 1, At, B1); PG8_BAR; PG8_SCHED;
	s_add_i32 s16, s45, s28
	v_lshl_add_u64 v[166:167], v[166:167], 0, s[70:71]
	s_mov_b32 m0, s16
	ds_read_b128 v[208:211], v170 offset:49152
	ds_read_b128 v[218:221], v170 offset:50176
	ds_read_b128 v[226:229], v170 offset:51200
	ds_read_b128 v[230:233], v170 offset:52224
	ds_read_b128 v[234:237], v170 offset:53248
	ds_read_b128 v[238:241], v170 offset:54272
	ds_read_b128 v[242:245], v170 offset:55296
	ds_read_b128 v[246:249], v170 offset:56320
	global_load_lds_dwordx4 v[166:167], off
	s_add_i32 m0, s16, 0x2000
	s_add_u32 s16, s20, 0x40080
	v_lshl_add_u64 v[166:167], v[180:181], 0, s[70:71]
	s_addc_u32 s17, s21, 0
	s_add_i32 s20, s46, s28
	global_load_lds_dwordx4 v[166:167], off
	v_lshl_add_u64 v[166:167], s[16:17], 0, v[34:35]
	s_mov_b32 m0, s20
	s_nop 0
	global_load_lds_dwordx4 v[166:167], off
	v_lshl_add_u64 v[166:167], s[16:17], 0, v[36:37]
	s_add_i32 m0, s20, 0x2000
	s_nop 0
	global_load_lds_dwordx4 v[166:167], off
	v_lshl_add_u64 v[166:167], v[202:203], 0, s[70:71]
	s_mov_b32 m0, s37
	s_nop 0
	global_load_lds_dwordx4 v[166:167], off
	v_lshl_add_u64 v[166:167], v[250:251], 0, s[70:71]
	s_mov_b32 m0, s38
	s_nop 0
	global_load_lds_dwordx4 v[166:167], off
	s_waitcnt vmcnt(8)
	s_waitcnt lgkmcnt(0)
	s_barrier
	s_setprio 1
	s_waitcnt lgkmcnt(0)
	v_mfma_f32_16x16x32_bf16 v[118:121], v[138:141], v[208:211], v[118:121]
	v_mfma_f32_16x16x32_bf16 v[86:89], v[172:175], v[208:211], v[86:89]
	v_mfma_f32_16x16x32_bf16 v[114:117], v[138:141], v[226:229], v[114:117]
	v_mfma_f32_16x16x32_bf16 v[78:81], v[172:175], v[226:229], v[78:81]
	v_mfma_f32_16x16x32_bf16 v[110:113], v[138:141], v[234:237], v[110:113]
	v_mfma_f32_16x16x32_bf16 v[70:73], v[172:175], v[234:237], v[70:73]
	v_mfma_f32_16x16x32_bf16 v[94:97], v[138:141], v[242:245], v[94:97]
	v_mfma_f32_16x16x32_bf16 v[62:65], v[172:175], v[242:245], v[62:65]
	v_mfma_f32_16x16x32_bf16 v[118:121], v[162:165], v[218:221], v[118:121]
	v_mfma_f32_16x16x32_bf16 v[86:89], v[176:179], v[218:221], v[86:89]
	v_mfma_f32_16x16x32_bf16 v[114:117], v[162:165], v[230:233], v[114:117]
	v_mfma_f32_16x16x32_bf16 v[78:81], v[176:179], v[230:233], v[78:81]
	v_mfma_f32_16x16x32_bf16 v[110:113], v[162:165], v[238:241], v[110:113]
	v_mfma_f32_16x16x32_bf16 v[70:73], v[176:179], v[238:241], v[70:73]
	v_mfma_f32_16x16x32_bf16 v[94:97], v[162:165], v[246:249], v[94:97]
	v_mfma_f32_16x16x32_bf16 v[62:65], v[176:179], v[246:249], v[62:65]
	s_setprio 0
	s_setprio 1
	v_mfma_f32_16x16x32_bf16 v[50:53], v[186:189], v[208:211], v[50:53]
	v_mfma_f32_16x16x32_bf16 v[14:17], v[194:197], v[208:211], v[14:17]
	v_mfma_f32_16x16x32_bf16 v[42:45], v[186:189], v[226:229], v[42:45]
	v_mfma_f32_16x16x32_bf16 v[10:13], v[194:197], v[226:229], v[10:13]
	v_mfma_f32_16x16x32_bf16 v[26:29], v[186:189], v[234:237], v[26:29]
	v_mfma_f32_16x16x32_bf16 v[6:9], v[194:197], v[234:237], v[6:9]
	v_mfma_f32_16x16x32_bf16 v[18:21], v[186:189], v[242:245], v[18:21]
	v_mfma_f32_16x16x32_bf16 v[2:5], v[194:197], v[242:245], v[2:5]
	v_mfma_f32_16x16x32_bf16 v[50:53], v[190:193], v[218:221], v[50:53]
	v_mfma_f32_16x16x32_bf16 v[14:17], v[198:201], v[218:221], v[14:17]
	v_mfma_f32_16x16x32_bf16 v[42:45], v[190:193], v[230:233], v[42:45]
	v_mfma_f32_16x16x32_bf16 v[10:13], v[198:201], v[230:233], v[10:13]
	v_mfma_f32_16x16x32_bf16 v[26:29], v[190:193], v[238:241], v[26:29]
	v_mfma_f32_16x16x32_bf16 v[6:9], v[198:201], v[238:241], v[6:9]
	v_mfma_f32_16x16x32_bf16 v[18:21], v[190:193], v[246:249], v[18:21]
	v_mfma_f32_16x16x32_bf16 v[2:5], v[198:201], v[246:249], v[2:5]
	s_setprio 0
	s_barrier
	s_add_i32 s44, s44, 2
	s_add_u32 s42, s42, 0x100
	s_addc_u32 s43, s43, 0
	s_cmp_gt_u32 s44, 13
	s_mov_b64 s[16:17], s[18:19]
	.p2align 3

;     __device__ __forceinline__ long arow(int pm) const { return (long)pm * BM; }
;     __device__ __forceinline__ long arow(int pm) const { if (pm < 132) { const int b = pm / 33, i = pm - b * 33; return (long)b * 8192 + 254 * i - 1; } return 32768 + (long)(pm - 132) * 256; }
;     __device__ __forceinline__ long arow(int p) const { return (long)p * BM; }
; #define PG8_STAGE(bufoff, gbase, voff) do { _Pragma("unroll") for (int _i = 0; _i < 2; ++_i) \
;         __builtin_amdgcn_global_load_lds((const unsigned*)((const char*)(gbase) + (voff)[_i]), (PG8_LAS unsigned*)(lds + (bufoff) + ldsw + _i * 8192), 16, 0, 0); } while (0)
; #define PG8_WAIT_V(n) asm volatile("s_waitcnt vmcnt(" #n ")" ::: "memory")
; #define PG8_BAR __builtin_amdgcn_s_barrier()
; template <class Epi, class Sched, bool ALIGN_EPI = false, bool SP2 = false>
; __device__ __forceinline__ void gemm_phase(PG8_LAS unsigned char* lds, const Gemm g, const Sched& S, const Epi& E) {
;     ...
;     f32x4 acc[2][2][4][2];
; #pragma unroll
;     for (int a = 0; a < 2; ++a)
; #pragma unroll
;         for (int b = 0; b < 2; ++b)
; #pragma unroll
;             for (int m = 0; m < 4; ++m)
; #pragma unroll
;                 for (int n = 0; n < 2; ++n) acc[a][b][m][n] = (f32x4){0.f, 0.f, 0.f, 0.f};
;     bf16x8 At[4][2], B0[2][2], B1[2][2];
;     const long rowb = (long)LD * 2;
;     const char* cA = (const char*)g.A + S.arow(cur.pm) * rowb; const char* cB = (const char*)g.Bt + (size_t)cur.pn * tstep;
;     S.a_ready(cur);
;     if constexpr (SP2) {
;         PG8_STAGE(PG8_SB(0, 0), cB, voffB); PG8_STAGE(PG8_SB(0, 1), cB + hstep, voffB); PG8_STAGE(PG8_SA(0, 0), cA, voffA); PG8_STAGE(PG8_SA(0, 1), cA + hstep, voffA);
;         if (wr == 1) PG8_BAR;
;         PG8_WAIT_V(2); PG8_BAR;
;         PG8_STAGE(PG8_SB(1, 0), cB + kstep, voffB); PG8_STAGE(PG8_SA(1, 0), cA + kstep, voffA); PG8_STAGE(PG8_SB(1, 1), cB + hstep + kstep, voffB);
;         PG8_WAIT_V(6); PG8_BAR;
;     } else {
;         PG8_STAGE(PG8_SB(0, 0), cB, voffB); PG8_STAGE(PG8_SA(0, 0), cA, voffA); PG8_STAGE(PG8_SB(0, 1), cB + hstep, voffB); PG8_STAGE(PG8_SA(0, 1), cA + hstep, voffA);
;         if (wr == 1) PG8_BAR;
;         PG8_WAIT_V(4); PG8_BAR;
;         PG8_STAGE(PG8_SB(1, 0), cB + kstep, voffB); PG8_STAGE(PG8_SA(1, 0), cA + kstep, voffA); PG8_STAGE(PG8_SB(1, 1), cB + hstep + kstep, voffB);
;         PG8_WAIT_V(6); PG8_BAR;
;     }
.LBB0_556:
	v_bfe_u32 v138, v2, 4, 2
	s_lshl_b32 s0, s0, 5
	v_and_b32_e32 v3, 15, v2
	v_lshlrev_b32_e32 v12, 4, v138
	v_lshlrev_b32_e32 v2, 2, v2
	s_and_b32 s20, s0, 0x60
	v_lshl_add_u64 v[4:5], s[60:61], 0, v[34:35]
	v_mov_b32_e32 v37, v35
	v_lshl_or_b32 v142, s1, 6, v3
	v_lshl_or_b32 v3, v3, 6, v12
	v_and_b32_e32 v2, 32, v2
	s_lshl_b32 s1, s1, 13
	s_lshl_b32 s0, s20, 7
	v_lshl_add_u64 v[6:7], s[60:61], 0, v[36:37]
	v_bitop3_b32 v139, v3, s0, v2 bitop3:0xde
	v_bitop3_b32 v12, v3, s1, v2 bitop3:0xde
	s_add_i32 m0, s16, 0x18000
	v_lshl_add_u64 v[2:3], v[4:5], 0, s[70:71]
	v_lshl_add_u64 v[8:9], s[62:63], 0, v[34:35]
	s_waitcnt vmcnt(2)
	s_barrier
	global_load_lds_dwordx4 v[2:3], off
	v_lshl_add_u64 v[2:3], v[6:7], 0, s[70:71]
	s_add_i32 m0, s16, 0x1a000
	s_add_i32 s21, s16, 0x8000
	v_lshl_add_u64 v[10:11], s[62:63], 0, v[36:37]
	global_load_lds_dwordx4 v[2:3], off
	v_lshl_add_u64 v[2:3], v[8:9], 0, s[70:71]
	s_mov_b32 m0, s21
	s_add_i32 s22, s16, 0xa000
	v_readlane_b32 s0, v253, 33
	global_load_lds_dwordx4 v[2:3], off
	v_lshl_add_u64 v[2:3], v[10:11], 0, s[70:71]
	s_mov_b32 m0, s22
	v_readlane_b32 s1, v253, 34
	global_load_lds_dwordx4 v[2:3], off
	s_add_i32 m0, s16, 0x1c000
	v_lshl_add_u64 v[2:3], s[0:1], 0, v[34:35]
	global_load_lds_dwordx4 v[2:3], off
	v_lshl_add_u64 v[2:3], s[0:1], 0, v[36:37]
	s_add_i32 m0, s16, 0x1e000
	s_mov_b32 s4, 0
	global_load_lds_dwordx4 v[2:3], off
	s_waitcnt vmcnt(6)
	v_mov_b32_e32 v2, 0
	s_mov_b64 s[0:1], -1
	s_mov_b64 s[2:3], 0
	v_add_u32_e32 v140, 0, v12
	v_mov_b32_e32 v3, v2
	v_mov_b32_e32 v4, v2
	v_mov_b32_e32 v5, v2
	s_waitcnt vmcnt(0)
	v_mov_b32_e32 v42, v2
	v_mov_b32_e32 v43, v2
	v_mov_b32_e32 v44, v2
	v_mov_b32_e32 v45, v2
	v_mov_b32_e32 v6, v2
	v_mov_b32_e32 v7, v2
	v_mov_b32_e32 v8, v2
	v_mov_b32_e32 v9, v2
	v_mov_b32_e32 v46, v2
	v_mov_b32_e32 v47, v2
	v_mov_b32_e32 v48, v2
	v_mov_b32_e32 v49, v2
	v_mov_b32_e32 v10, v2
	v_mov_b32_e32 v11, v2
	v_mov_b32_e32 v12, v2
	v_mov_b32_e32 v13, v2
	v_mov_b32_e32 v50, v2
	v_mov_b32_e32 v51, v2
	v_mov_b32_e32 v52, v2
	v_mov_b32_e32 v53, v2
	v_mov_b32_e32 v14, v2
	v_mov_b32_e32 v15, v2
	v_mov_b32_e32 v16, v2
	v_mov_b32_e32 v17, v2
	v_mov_b32_e32 v54, v2
	v_mov_b32_e32 v55, v2
	v_mov_b32_e32 v56, v2
	v_mov_b32_e32 v57, v2
	v_mov_b32_e32 v74, v2
	v_mov_b32_e32 v75, v2
	v_mov_b32_e32 v76, v2
	v_mov_b32_e32 v77, v2
	v_mov_b32_e32 v106, v2
	v_mov_b32_e32 v107, v2
	v_mov_b32_e32 v108, v2
	v_mov_b32_e32 v109, v2
	v_mov_b32_e32 v78, v2
	v_mov_b32_e32 v79, v2
	v_mov_b32_e32 v80, v2
	v_mov_b32_e32 v81, v2
	v_mov_b32_e32 v110, v2
	v_mov_b32_e32 v111, v2
	v_mov_b32_e32 v112, v2
	v_mov_b32_e32 v113, v2
	v_mov_b32_e32 v82, v2
	v_mov_b32_e32 v83, v2
	v_mov_b32_e32 v84, v2
	v_mov_b32_e32 v85, v2
	v_mov_b32_e32 v114, v2
	v_mov_b32_e32 v115, v2
	v_mov_b32_e32 v116, v2
	v_mov_b32_e32 v117, v2
	v_mov_b32_e32 v86, v2
	v_mov_b32_e32 v87, v2
	v_mov_b32_e32 v88, v2
	v_mov_b32_e32 v89, v2
	v_mov_b32_e32 v118, v2
	v_mov_b32_e32 v119, v2
	v_mov_b32_e32 v120, v2
	v_mov_b32_e32 v121, v2
	v_mov_b32_e32 v18, v2
	v_mov_b32_e32 v19, v2
	v_mov_b32_e32 v20, v2
	v_mov_b32_e32 v21, v2
	v_mov_b32_e32 v58, v2
	v_mov_b32_e32 v59, v2
	v_mov_b32_e32 v60, v2
	v_mov_b32_e32 v61, v2
	v_mov_b32_e32 v22, v2
	v_mov_b32_e32 v23, v2
	v_mov_b32_e32 v24, v2
	v_mov_b32_e32 v25, v2
	v_mov_b32_e32 v62, v2
	v_mov_b32_e32 v63, v2
	v_mov_b32_e32 v64, v2
	v_mov_b32_e32 v65, v2
	v_mov_b32_e32 v26, v2
	v_mov_b32_e32 v27, v2
	v_mov_b32_e32 v28, v2
	v_mov_b32_e32 v29, v2
	v_mov_b32_e32 v66, v2
	v_mov_b32_e32 v67, v2
	v_mov_b32_e32 v68, v2
	v_mov_b32_e32 v69, v2
	v_mov_b32_e32 v30, v2
	v_mov_b32_e32 v31, v2
	v_mov_b32_e32 v32, v2
	v_mov_b32_e32 v33, v2
	v_mov_b32_e32 v70, v2
	v_mov_b32_e32 v71, v2
	v_mov_b32_e32 v72, v2
	v_mov_b32_e32 v73, v2
	v_mov_b32_e32 v90, v2
	v_mov_b32_e32 v91, v2
	v_mov_b32_e32 v92, v2
	v_mov_b32_e32 v93, v2
	v_mov_b32_e32 v122, v2
	v_mov_b32_e32 v123, v2
	v_mov_b32_e32 v124, v2
	v_mov_b32_e32 v125, v2
	v_mov_b32_e32 v94, v2
	v_mov_b32_e32 v95, v2
	v_mov_b32_e32 v96, v2
	v_mov_b32_e32 v97, v2
	v_mov_b32_e32 v126, v2
	v_mov_b32_e32 v127, v2
	v_mov_b32_e32 v128, v2
	v_mov_b32_e32 v129, v2
	v_mov_b32_e32 v98, v2
	v_mov_b32_e32 v99, v2
	v_mov_b32_e32 v100, v2
	v_mov_b32_e32 v101, v2
	v_mov_b32_e32 v130, v2
	v_mov_b32_e32 v131, v2
	v_mov_b32_e32 v132, v2
	v_mov_b32_e32 v133, v2
	v_mov_b32_e32 v102, v2
	v_mov_b32_e32 v103, v2
	v_mov_b32_e32 v104, v2
	v_mov_b32_e32 v105, v2
	v_mov_b32_e32 v134, v2
	v_mov_b32_e32 v135, v2
	v_mov_b32_e32 v136, v2
	v_mov_b32_e32 v137, v2
	s_barrier
	.p2align 3

;     __device__ __forceinline__ long arow(int pm) const { return (long)pm * BM; }
;     __device__ __forceinline__ long arow(int pm) const { if (pm < 132) { const int b = pm / 33, i = pm - b * 33; return (long)b * 8192 + 254 * i - 1; } return 32768 + (long)(pm - 132) * 256; }
;     __device__ __forceinline__ bool next(int i, Unit& u) const { if (i > 0) return false; u.pm = pm; u.pn = pn; return true; }
;     __device__ __forceinline__ long arow(int p) const { return (long)p * BM; }
; #define PG8_STAGE(bufoff, gbase, voff) do { _Pragma("unroll") for (int _i = 0; _i < 2; ++_i) \
;         __builtin_amdgcn_global_load_lds((const unsigned*)((const char*)(gbase) + (voff)[_i]), (PG8_LAS unsigned*)(lds + (bufoff) + ldsw + _i * 8192), 16, 0, 0); } while (0)
; #define PG8_LDA(dst, b, h) do { _Pragma("unroll") for (int m = 0; m < 4; ++m) _Pragma("unroll") for (int k = 0; k < 2; ++k) dst[m][k] = *(const PG8_LAS bf16x8*)(lds + PG8_SA(b, h) + aoff + m * 2048 + k * 1024); } while (0)
; template <class Epi, class Sched, bool ALIGN_EPI = false, bool SP2 = false>
; __device__ __forceinline__ void gemm_phase(PG8_LAS unsigned char* lds, const Gemm g, const Sched& S, const Epi& E) {
;     ...
;         const bool has_next = S.next(ui + 1, nxt);
;         const char* nA = has_next ? (const char*)g.A + S.arow(nxt.pm) * rowb : cA; const char* nB = has_next ? (const char*)g.Bt + (size_t)nxt.pn * tstep : cB;
;         for (int t = 0; t < nt; t += 2) {
;             const bool last = (t == nt - 2);
;             const char* a1 = cA + (size_t)(t + 1) * kstep;
;             const char* a2 = last ? nA : cA + (size_t)(t + 2) * kstep; const char* b2 = last ? nB : cB + (size_t)(t + 2) * kstep;
;             const char* a3 = a2 + kstep; const char* b3 = b2 + kstep;
;             if (last && has_next) S.a_ready(nxt);
;             if constexpr (SP2) {
;             PG8_LDB(B0, 0, 0); PG8_LDB(B1, 0, 1); PG8_SCHED; PG8_LDA(At, 0, 0); PG8_STAGE(PG8_SA(1, 1), a1 + hstep, voffA);
;             PG8_WAIT_V(8); PG8_WAIT_L(0); PG8_BAR; PG8_MMA(0, 0, At, B0); PG8_MMA(0, 1, At, B1); PG8_BAR; PG8_SCHED;
;             PG8_LDA(At, 0, 1); PG8_STAGE(PG8_SB(0, 0), b2, voffB); PG8_STAGE(PG8_SB(0, 1), b2 + hstep, voffB); PG8_STAGE(PG8_SA(0, 0), a2, voffA);
;             PG8_WAIT_V(8); PG8_WAIT_L(0); PG8_BAR; PG8_MMA(1, 0, At, B0); PG8_MMA(1, 1, At, B1); PG8_BAR; PG8_SCHED;
.LBB0_696:
	s_ashr_i32 s93, s92, 31
	s_lshl_b64 s[14:15], s[92:93], 19
	v_readlane_b32 s3, v255, 9
	s_add_u32 s96, s3, s14
	v_readlane_b32 s3, v255, 11
	s_addc_u32 s97, s3, s15
	s_and_b64 s[0:1], s[0:1], exec
	s_cselect_b32 s3, s97, s11
	s_cselect_b32 s14, s96, s10
	s_add_u32 s0, s12, 0x40080
	s_addc_u32 s1, s13, 0
	s_add_u32 s15, s10, 0x100
	s_addc_u32 s16, s11, 0
	s_mov_b32 s17, -2
	s_waitcnt vmcnt(0)
	s_add_u32 s10, s0, 0xfffc0080
	s_addc_u32 s11, s1, -1
	s_add_i32 s19, 0, 0x10000
	s_cmp_eq_u32 s17, 12
	s_cselect_b32 s13, s95, s11
	s_cselect_b32 s12, s94, s10
	v_add_u32_e32 v38, s19, v228
	s_cselect_b32 s11, s3, s16
	s_cselect_b32 s10, s14, s15
	s_add_i32 s22, 0, 0x14000
	ds_read_b128 v[106:109], v38
	ds_read_b128 v[110:113], v38 offset:1024
	ds_read_b128 v[114:117], v38 offset:2048
	ds_read_b128 v[118:121], v38 offset:3072
	v_add_u32_e32 v38, s22, v228
	ds_read_b128 v[122:125], v38
	ds_read_b128 v[126:129], v38 offset:1024
	ds_read_b128 v[130:133], v38 offset:2048
	ds_read_b128 v[134:137], v38 offset:3072
	s_add_i32 m0, s80, 0xc000
	ds_read_b128 v[170:173], v242
	ds_read_b128 v[174:177], v242 offset:1024
	ds_read_b128 v[178:181], v242 offset:2048
	ds_read_b128 v[194:197], v242 offset:3072
	ds_read_b128 v[198:201], v242 offset:4096
	ds_read_b128 v[208:211], v242 offset:5120
	ds_read_b128 v[218:221], v242 offset:6144
	ds_read_b128 v[244:247], v242 offset:7168
	global_load_lds_dwordx4 v190, s[0:1]
	s_add_i32 m0, s80, 0xe000
	s_nop 0
	global_load_lds_dwordx4 v192, s[0:1]
	s_waitcnt vmcnt(8)
	s_waitcnt lgkmcnt(0)
	s_barrier
	s_setprio 1
	s_waitcnt lgkmcnt(0)
	v_mfma_f32_16x16x32_bf16 v[166:169], v[106:109], v[170:173], 0
	v_mfma_f32_16x16x32_bf16 v[70:73], v[114:117], v[170:173], 0
	v_mfma_f32_16x16x32_bf16 v[158:161], v[106:109], v[178:181], 0
	v_mfma_f32_16x16x32_bf16 v[62:65], v[114:117], v[178:181], 0
	v_mfma_f32_16x16x32_bf16 v[150:153], v[106:109], v[198:201], 0
	v_mfma_f32_16x16x32_bf16 v[54:57], v[114:117], v[198:201], 0
	v_mfma_f32_16x16x32_bf16 v[142:145], v[106:109], v[218:221], 0
	v_mfma_f32_16x16x32_bf16 v[46:49], v[114:117], v[218:221], 0
	v_mfma_f32_16x16x32_bf16 v[166:169], v[110:113], v[174:177], v[166:169]
	v_mfma_f32_16x16x32_bf16 v[70:73], v[118:121], v[174:177], v[70:73]
	v_mfma_f32_16x16x32_bf16 v[158:161], v[110:113], v[194:197], v[158:161]
	v_mfma_f32_16x16x32_bf16 v[62:65], v[118:121], v[194:197], v[62:65]
	v_mfma_f32_16x16x32_bf16 v[150:153], v[110:113], v[208:211], v[150:153]
	v_mfma_f32_16x16x32_bf16 v[54:57], v[118:121], v[208:211], v[54:57]
	v_mfma_f32_16x16x32_bf16 v[142:145], v[110:113], v[244:247], v[142:145]
	v_mfma_f32_16x16x32_bf16 v[46:49], v[118:121], v[244:247], v[46:49]
	s_setprio 0
	s_setprio 1
	v_mfma_f32_16x16x32_bf16 v[162:165], v[122:125], v[170:173], 0
	v_mfma_f32_16x16x32_bf16 v[66:69], v[130:133], v[170:173], 0
	v_mfma_f32_16x16x32_bf16 v[154:157], v[122:125], v[178:181], 0
	v_mfma_f32_16x16x32_bf16 v[58:61], v[130:133], v[178:181], 0
	v_mfma_f32_16x16x32_bf16 v[146:149], v[122:125], v[198:201], 0
	v_mfma_f32_16x16x32_bf16 v[50:53], v[130:133], v[198:201], 0
	v_mfma_f32_16x16x32_bf16 v[138:141], v[122:125], v[218:221], 0
	v_mfma_f32_16x16x32_bf16 v[42:45], v[130:133], v[218:221], 0
	v_mfma_f32_16x16x32_bf16 v[162:165], v[126:129], v[174:177], v[162:165]
	v_mfma_f32_16x16x32_bf16 v[66:69], v[134:137], v[174:177], v[66:69]
	v_mfma_f32_16x16x32_bf16 v[154:157], v[126:129], v[194:197], v[154:157]
	v_mfma_f32_16x16x32_bf16 v[58:61], v[134:137], v[194:197], v[58:61]
	v_mfma_f32_16x16x32_bf16 v[146:149], v[126:129], v[208:211], v[146:149]
	v_mfma_f32_16x16x32_bf16 v[50:53], v[134:137], v[208:211], v[50:53]
	v_mfma_f32_16x16x32_bf16 v[138:141], v[126:129], v[244:247], v[138:141]
	v_mfma_f32_16x16x32_bf16 v[42:45], v[134:137], v[244:247], v[42:45]
	s_setprio 0
	s_barrier
	s_add_i32 s19, s19, s59
	v_lshl_add_u64 v[202:203], s[10:11], 0, v[34:35]
	s_mov_b32 m0, s19
	ds_read_b128 v[170:173], v242 offset:16384
	ds_read_b128 v[174:177], v242 offset:17408
	ds_read_b128 v[178:181], v242 offset:18432
	ds_read_b128 v[194:197], v242 offset:19456
	ds_read_b128 v[198:201], v242 offset:20480
	ds_read_b128 v[208:211], v242 offset:21504
	ds_read_b128 v[218:221], v242 offset:22528
	ds_read_b128 v[244:247], v242 offset:23552
	global_load_lds_dwordx4 v[202:203], off
	s_add_i32 m0, s19, 0x2000
	s_add_u32 s20, s10, 0x40000
	v_lshl_add_u64 v[212:213], s[10:11], 0, v[188:189]
	s_addc_u32 s21, s11, 0
	s_add_i32 s19, s22, s59
	global_load_lds_dwordx4 v[212:213], off
	s_mov_b32 m0, s19
	v_lshl_add_u64 v[250:251], s[12:13], 0, v[186:187]
	global_load_lds_dwordx4 v34, s[20:21]
	s_add_i32 m0, s19, 0x2000
	s_nop 0
	global_load_lds_dwordx4 v188, s[20:21]
	v_lshl_add_u64 v[248:249], s[12:13], 0, v[36:37]
	s_mov_b32 m0, s80
	s_nop 0
	global_load_lds_dwordx4 v[248:249], off
	s_mov_b32 m0, s81
	s_nop 0
	global_load_lds_dwordx4 v[250:251], off
	s_waitcnt vmcnt(8)
	s_waitcnt lgkmcnt(0)
	s_barrier
; #define PG8_STAGE(bufoff, gbase, voff) do { _Pragma("unroll") for (int _i = 0; _i < 2; ++_i) \
;         __builtin_amdgcn_global_load_lds((const unsigned*)((const char*)(gbase) + (voff)[_i]), (PG8_LAS unsigned*)(lds + (bufoff) + ldsw + _i * 8192), 16, 0, 0); } while (0)
; #define PG8_LDA(dst, b, h) do { _Pragma("unroll") for (int m = 0; m < 4; ++m) _Pragma("unroll") for (int k = 0; k < 2; ++k) dst[m][k] = *(const PG8_LAS bf16x8*)(lds + PG8_SA(b, h) + aoff + m * 2048 + k * 1024); } while (0)
; #define PG8_LDB(dst, b, h) do { _Pragma("unroll") for (int n = 0; n < 2; ++n) _Pragma("unroll") for (int k = 0; k < 2; ++k) dst[n][k] = *(const PG8_LAS bf16x8*)(lds + PG8_SB(b, h) + boff + n * 2048 + k * 1024); } while (0)
; #define PG8_MMA(ai, bj, At, Bt) do { __builtin_amdgcn_s_setprio(1); _Pragma("unroll") for (int m = 0; m < 4; ++m) _Pragma("unroll") for (int n = 0; n < 2; ++n) _Pragma("unroll") for (int k = 0; k < 2; ++k) \
;         acc[ai][bj][m][n] = __builtin_amdgcn_mfma_f32_16x16x32_bf16(Bt[n][k], At[m][k], acc[ai][bj][m][n], 0, 0, 0); __builtin_amdgcn_s_setprio(0); } while (0)
; #define PG8_WAIT_V(n) asm volatile("s_waitcnt vmcnt(" #n ")" ::: "memory")
; #define PG8_WAIT_L(n) asm volatile("s_waitcnt lgkmcnt(" #n ")" ::: "memory")
; #define PG8_BAR __builtin_amdgcn_s_barrier()
; #define PG8_SCHED __builtin_amdgcn_sched_barrier(0)
; template <class Epi, class Sched, bool ALIGN_EPI = false, bool SP2 = false>
; __device__ __forceinline__ void gemm_phase(PG8_LAS unsigned char* lds, const Gemm g, const Sched& S, const Epi& E) {
;     ...
;             PG8_WAIT_V(8); PG8_WAIT_L(0); PG8_BAR; PG8_MMA(1, 0, At, B0); PG8_MMA(1, 1, At, B1); PG8_BAR; PG8_SCHED;
;             PG8_LDB(B0, 1, 0); PG8_LDB(B1, 1, 1); PG8_SCHED; PG8_LDA(At, 1, 0); PG8_STAGE(PG8_SA(0, 1), a2 + hstep, voffA);
;             PG8_WAIT_V(8); PG8_WAIT_L(0); PG8_BAR; PG8_MMA(0, 0, At, B0); PG8_MMA(0, 1, At, B1); PG8_BAR; PG8_SCHED;
	s_setprio 1
	s_waitcnt lgkmcnt(0)
	v_mfma_f32_16x16x32_bf16 v[102:105], v[106:109], v[170:173], 0
	v_mfma_f32_16x16x32_bf16 v[30:33], v[114:117], v[170:173], 0
	v_mfma_f32_16x16x32_bf16 v[94:97], v[106:109], v[178:181], 0
	v_mfma_f32_16x16x32_bf16 v[22:25], v[114:117], v[178:181], 0
	v_mfma_f32_16x16x32_bf16 v[86:89], v[106:109], v[198:201], 0
	v_mfma_f32_16x16x32_bf16 v[14:17], v[114:117], v[198:201], 0
	v_mfma_f32_16x16x32_bf16 v[78:81], v[106:109], v[218:221], 0
	v_mfma_f32_16x16x32_bf16 v[6:9], v[114:117], v[218:221], 0
	v_mfma_f32_16x16x32_bf16 v[102:105], v[110:113], v[174:177], v[102:105]
	v_mfma_f32_16x16x32_bf16 v[30:33], v[118:121], v[174:177], v[30:33]
	v_mfma_f32_16x16x32_bf16 v[94:97], v[110:113], v[194:197], v[94:97]
	v_mfma_f32_16x16x32_bf16 v[22:25], v[118:121], v[194:197], v[22:25]
	v_mfma_f32_16x16x32_bf16 v[86:89], v[110:113], v[208:211], v[86:89]
	v_mfma_f32_16x16x32_bf16 v[14:17], v[118:121], v[208:211], v[14:17]
	v_mfma_f32_16x16x32_bf16 v[78:81], v[110:113], v[244:247], v[78:81]
	v_mfma_f32_16x16x32_bf16 v[6:9], v[118:121], v[244:247], v[6:9]
	s_setprio 0
	s_setprio 1
	v_mfma_f32_16x16x32_bf16 v[98:101], v[122:125], v[170:173], 0
	v_mfma_f32_16x16x32_bf16 v[26:29], v[130:133], v[170:173], 0
	v_mfma_f32_16x16x32_bf16 v[90:93], v[122:125], v[178:181], 0
	v_mfma_f32_16x16x32_bf16 v[18:21], v[130:133], v[178:181], 0
	v_mfma_f32_16x16x32_bf16 v[82:85], v[122:125], v[198:201], 0
	v_mfma_f32_16x16x32_bf16 v[10:13], v[130:133], v[198:201], 0
	v_mfma_f32_16x16x32_bf16 v[74:77], v[122:125], v[218:221], 0
	v_mfma_f32_16x16x32_bf16 v[2:5], v[130:133], v[218:221], 0
	v_mfma_f32_16x16x32_bf16 v[98:101], v[126:129], v[174:177], v[98:101]
	v_mfma_f32_16x16x32_bf16 v[26:29], v[134:137], v[174:177], v[26:29]
	v_mfma_f32_16x16x32_bf16 v[90:93], v[126:129], v[194:197], v[90:93]
	v_mfma_f32_16x16x32_bf16 v[18:21], v[134:137], v[194:197], v[18:21]
	v_mfma_f32_16x16x32_bf16 v[82:85], v[126:129], v[208:211], v[82:85]
	v_mfma_f32_16x16x32_bf16 v[10:13], v[134:137], v[208:211], v[10:13]
	v_mfma_f32_16x16x32_bf16 v[74:77], v[126:129], v[244:247], v[74:77]
	v_mfma_f32_16x16x32_bf16 v[2:5], v[134:137], v[244:247], v[2:5]
	s_setprio 0
	s_barrier
	s_add_i32 s19, 0, 0x18000
	v_add_u32_e32 v38, s19, v228
	s_add_i32 s20, 0, 0x1c000
	ds_read_b128 v[106:109], v38
	ds_read_b128 v[110:113], v38 offset:1024
	ds_read_b128 v[114:117], v38 offset:2048
	ds_read_b128 v[118:121], v38 offset:3072
	v_add_u32_e32 v38, s20, v228
	ds_read_b128 v[122:125], v38
	ds_read_b128 v[126:129], v38 offset:1024
	ds_read_b128 v[130:133], v38 offset:2048
	ds_read_b128 v[134:137], v38 offset:3072
	s_add_u32 s12, s12, 0x40000
	s_addc_u32 s13, s13, 0
	s_mov_b32 m0, s76
	ds_read_b128 v[170:173], v242 offset:32768
	ds_read_b128 v[174:177], v242 offset:33792
	ds_read_b128 v[178:181], v242 offset:34816
	ds_read_b128 v[194:197], v242 offset:35840
	ds_read_b128 v[198:201], v242 offset:36864
	ds_read_b128 v[208:211], v242 offset:37888
	ds_read_b128 v[218:221], v242 offset:38912
	ds_read_b128 v[244:247], v242 offset:39936
	global_load_lds_dwordx4 v36, s[12:13]
	s_mov_b32 m0, s77
	s_nop 0
	global_load_lds_dwordx4 v186, s[12:13]
	s_waitcnt vmcnt(8)
	s_waitcnt lgkmcnt(0)
	s_barrier
	s_setprio 1
	s_waitcnt lgkmcnt(0)
	v_mfma_f32_16x16x32_bf16 v[166:169], v[106:109], v[170:173], v[166:169]
	v_mfma_f32_16x16x32_bf16 v[70:73], v[114:117], v[170:173], v[70:73]
	v_mfma_f32_16x16x32_bf16 v[158:161], v[106:109], v[178:181], v[158:161]
	v_mfma_f32_16x16x32_bf16 v[62:65], v[114:117], v[178:181], v[62:65]
	v_mfma_f32_16x16x32_bf16 v[150:153], v[106:109], v[198:201], v[150:153]
	v_mfma_f32_16x16x32_bf16 v[54:57], v[114:117], v[198:201], v[54:57]
	v_mfma_f32_16x16x32_bf16 v[142:145], v[106:109], v[218:221], v[142:145]
	v_mfma_f32_16x16x32_bf16 v[46:49], v[114:117], v[218:221], v[46:49]
	v_mfma_f32_16x16x32_bf16 v[166:169], v[110:113], v[174:177], v[166:169]
	v_mfma_f32_16x16x32_bf16 v[70:73], v[118:121], v[174:177], v[70:73]
	v_mfma_f32_16x16x32_bf16 v[158:161], v[110:113], v[194:197], v[158:161]
	v_mfma_f32_16x16x32_bf16 v[62:65], v[118:121], v[194:197], v[62:65]
	v_mfma_f32_16x16x32_bf16 v[150:153], v[110:113], v[208:211], v[150:153]
	v_mfma_f32_16x16x32_bf16 v[54:57], v[118:121], v[208:211], v[54:57]
	v_mfma_f32_16x16x32_bf16 v[142:145], v[110:113], v[244:247], v[142:145]
	v_mfma_f32_16x16x32_bf16 v[46:49], v[118:121], v[244:247], v[46:49]
	s_setprio 0
	s_setprio 1
	v_mfma_f32_16x16x32_bf16 v[162:165], v[122:125], v[170:173], v[162:165]
	v_mfma_f32_16x16x32_bf16 v[66:69], v[130:133], v[170:173], v[66:69]
	v_mfma_f32_16x16x32_bf16 v[154:157], v[122:125], v[178:181], v[154:157]
	v_mfma_f32_16x16x32_bf16 v[58:61], v[130:133], v[178:181], v[58:61]
	v_mfma_f32_16x16x32_bf16 v[146:149], v[122:125], v[198:201], v[146:149]
	v_mfma_f32_16x16x32_bf16 v[50:53], v[130:133], v[198:201], v[50:53]
	v_mfma_f32_16x16x32_bf16 v[138:141], v[122:125], v[218:221], v[138:141]
	v_mfma_f32_16x16x32_bf16 v[42:45], v[130:133], v[218:221], v[42:45]
	v_mfma_f32_16x16x32_bf16 v[162:165], v[126:129], v[174:177], v[162:165]
	v_mfma_f32_16x16x32_bf16 v[66:69], v[134:137], v[174:177], v[66:69]
	v_mfma_f32_16x16x32_bf16 v[154:157], v[126:129], v[194:197], v[154:157]
	v_mfma_f32_16x16x32_bf16 v[58:61], v[134:137], v[194:197], v[58:61]
	v_mfma_f32_16x16x32_bf16 v[146:149], v[126:129], v[208:211], v[146:149]
	v_mfma_f32_16x16x32_bf16 v[50:53], v[134:137], v[208:211], v[50:53]
	v_mfma_f32_16x16x32_bf16 v[138:141], v[126:129], v[244:247], v[138:141]
	v_mfma_f32_16x16x32_bf16 v[42:45], v[134:137], v[244:247], v[42:45]
	s_setprio 0
	s_barrier
; #define PG8_STAGE(bufoff, gbase, voff) do { _Pragma("unroll") for (int _i = 0; _i < 2; ++_i) \
;         __builtin_amdgcn_global_load_lds((const unsigned*)((const char*)(gbase) + (voff)[_i]), (PG8_LAS unsigned*)(lds + (bufoff) + ldsw + _i * 8192), 16, 0, 0); } while (0)
; #define PG8_LDA(dst, b, h) do { _Pragma("unroll") for (int m = 0; m < 4; ++m) _Pragma("unroll") for (int k = 0; k < 2; ++k) dst[m][k] = *(const PG8_LAS bf16x8*)(lds + PG8_SA(b, h) + aoff + m * 2048 + k * 1024); } while (0)
; #define PG8_LDB(dst, b, h) do { _Pragma("unroll") for (int n = 0; n < 2; ++n) _Pragma("unroll") for (int k = 0; k < 2; ++k) dst[n][k] = *(const PG8_LAS bf16x8*)(lds + PG8_SB(b, h) + boff + n * 2048 + k * 1024); } while (0)
; #define PG8_MMA(ai, bj, At, Bt) do { __builtin_amdgcn_s_setprio(1); _Pragma("unroll") for (int m = 0; m < 4; ++m) _Pragma("unroll") for (int n = 0; n < 2; ++n) _Pragma("unroll") for (int k = 0; k < 2; ++k) \
;         acc[ai][bj][m][n] = __builtin_amdgcn_mfma_f32_16x16x32_bf16(Bt[n][k], At[m][k], acc[ai][bj][m][n], 0, 0, 0); __builtin_amdgcn_s_setprio(0); } while (0)
; #define PG8_WAIT_V(n) asm volatile("s_waitcnt vmcnt(" #n ")" ::: "memory")
; #define PG8_WAIT_L(n) asm volatile("s_waitcnt lgkmcnt(" #n ")" ::: "memory")
; #define PG8_BAR __builtin_amdgcn_s_barrier()
; #define PG8_SCHED __builtin_amdgcn_sched_barrier(0)
; template <class Epi, class Sched, bool ALIGN_EPI = false, bool SP2 = false>
; __device__ __forceinline__ void gemm_phase(PG8_LAS unsigned char* lds, const Gemm g, const Sched& S, const Epi& E) {
;     ...
;         for (int t = 0; t < nt; t += 2) {
;     ...
;             PG8_LDB(B0, 1, 0); PG8_LDB(B1, 1, 1); PG8_SCHED; PG8_LDA(At, 1, 0); PG8_STAGE(PG8_SA(0, 1), a2 + hstep, voffA);
;             PG8_WAIT_V(8); PG8_WAIT_L(0); PG8_BAR; PG8_MMA(0, 0, At, B0); PG8_MMA(0, 1, At, B1); PG8_BAR; PG8_SCHED;
;             PG8_LDA(At, 1, 1); PG8_STAGE(PG8_SB(1, 0), b3, voffB); PG8_STAGE(PG8_SB(1, 1), b3 + hstep, voffB); PG8_STAGE(PG8_SA(1, 0), a3, voffA);
;             PG8_WAIT_V(8); PG8_WAIT_L(0); PG8_BAR; PG8_MMA(1, 0, At, B0); PG8_MMA(1, 1, At, B1); PG8_BAR; PG8_SCHED;
	s_add_i32 s12, s19, s59
	v_lshl_add_u64 v[38:39], v[202:203], 0, s[70:71]
	s_mov_b32 m0, s12
	ds_read_b128 v[170:173], v242 offset:49152
	ds_read_b128 v[174:177], v242 offset:50176
	ds_read_b128 v[178:181], v242 offset:51200
	ds_read_b128 v[194:197], v242 offset:52224
	ds_read_b128 v[198:201], v242 offset:53248
	ds_read_b128 v[208:211], v242 offset:54272
	ds_read_b128 v[218:221], v242 offset:55296
	ds_read_b128 v[244:247], v242 offset:56320
	global_load_lds_dwordx4 v[38:39], off
	s_add_i32 m0, s12, 0x2000
	s_add_u32 s10, s10, 0x40080
	v_lshl_add_u64 v[38:39], v[212:213], 0, s[70:71]
	s_addc_u32 s11, s11, 0
	s_add_i32 s12, s20, s59
	global_load_lds_dwordx4 v[38:39], off
	s_mov_b32 m0, s12
	s_nop 0
	global_load_lds_dwordx4 v34, s[10:11]
	s_add_i32 m0, s12, 0x2000
	s_nop 0
	global_load_lds_dwordx4 v188, s[10:11]
	v_lshl_add_u64 v[38:39], v[248:249], 0, s[70:71]
	s_mov_b32 m0, s82
	s_nop 0
	global_load_lds_dwordx4 v[38:39], off
	v_lshl_add_u64 v[38:39], v[250:251], 0, s[70:71]
	s_mov_b32 m0, s83
	s_nop 0
	global_load_lds_dwordx4 v[38:39], off
	s_waitcnt vmcnt(8)
	s_waitcnt lgkmcnt(0)
	s_barrier
	s_setprio 1
	s_waitcnt lgkmcnt(0)
	v_mfma_f32_16x16x32_bf16 v[102:105], v[106:109], v[170:173], v[102:105]
	v_mfma_f32_16x16x32_bf16 v[30:33], v[114:117], v[170:173], v[30:33]
	v_mfma_f32_16x16x32_bf16 v[94:97], v[106:109], v[178:181], v[94:97]
	v_mfma_f32_16x16x32_bf16 v[22:25], v[114:117], v[178:181], v[22:25]
	v_mfma_f32_16x16x32_bf16 v[86:89], v[106:109], v[198:201], v[86:89]
	v_mfma_f32_16x16x32_bf16 v[14:17], v[114:117], v[198:201], v[14:17]
	v_mfma_f32_16x16x32_bf16 v[78:81], v[106:109], v[218:221], v[78:81]
	v_mfma_f32_16x16x32_bf16 v[6:9], v[114:117], v[218:221], v[6:9]
	v_mfma_f32_16x16x32_bf16 v[102:105], v[110:113], v[174:177], v[102:105]
	v_mfma_f32_16x16x32_bf16 v[30:33], v[118:121], v[174:177], v[30:33]
	v_mfma_f32_16x16x32_bf16 v[94:97], v[110:113], v[194:197], v[94:97]
	v_mfma_f32_16x16x32_bf16 v[22:25], v[118:121], v[194:197], v[22:25]
	v_mfma_f32_16x16x32_bf16 v[86:89], v[110:113], v[208:211], v[86:89]
	v_mfma_f32_16x16x32_bf16 v[14:17], v[118:121], v[208:211], v[14:17]
	v_mfma_f32_16x16x32_bf16 v[78:81], v[110:113], v[244:247], v[78:81]
	v_mfma_f32_16x16x32_bf16 v[6:9], v[118:121], v[244:247], v[6:9]
	s_setprio 0
	s_setprio 1
	v_mfma_f32_16x16x32_bf16 v[98:101], v[122:125], v[170:173], v[98:101]
	v_mfma_f32_16x16x32_bf16 v[26:29], v[130:133], v[170:173], v[26:29]
	v_mfma_f32_16x16x32_bf16 v[90:93], v[122:125], v[178:181], v[90:93]
	v_mfma_f32_16x16x32_bf16 v[18:21], v[130:133], v[178:181], v[18:21]
	v_mfma_f32_16x16x32_bf16 v[82:85], v[122:125], v[198:201], v[82:85]
	v_mfma_f32_16x16x32_bf16 v[10:13], v[130:133], v[198:201], v[10:13]
	v_mfma_f32_16x16x32_bf16 v[74:77], v[122:125], v[218:221], v[74:77]
	v_mfma_f32_16x16x32_bf16 v[2:5], v[130:133], v[218:221], v[2:5]
	v_mfma_f32_16x16x32_bf16 v[98:101], v[126:129], v[174:177], v[98:101]
	v_mfma_f32_16x16x32_bf16 v[26:29], v[134:137], v[174:177], v[26:29]
	v_mfma_f32_16x16x32_bf16 v[90:93], v[126:129], v[194:197], v[90:93]
	v_mfma_f32_16x16x32_bf16 v[18:21], v[134:137], v[194:197], v[18:21]
	v_mfma_f32_16x16x32_bf16 v[82:85], v[126:129], v[208:211], v[82:85]
	v_mfma_f32_16x16x32_bf16 v[10:13], v[134:137], v[208:211], v[10:13]
	v_mfma_f32_16x16x32_bf16 v[74:77], v[126:129], v[244:247], v[74:77]
	v_mfma_f32_16x16x32_bf16 v[2:5], v[134:137], v[244:247], v[2:5]
	s_setprio 0
	s_barrier
	s_add_i32 s17, s17, 2
	s_add_u32 s0, s0, 0x100
	s_addc_u32 s1, s1, 0
	s_add_u32 s15, s15, 0x100
	s_addc_u32 s16, s16, 0
	s_cmp_gt_u32 s17, 13
	.p2align 3

;     __device__ __forceinline__ long arow(int pm) const { return (long)pm * BM; }
;     __device__ __forceinline__ long arow(int pm) const { if (pm < 132) { const int b = pm / 33, i = pm - b * 33; return (long)b * 8192 + 254 * i - 1; } return 32768 + (long)(pm - 132) * 256; }
;     __device__ __forceinline__ bool next(int i, Unit& u) const { if (i > 0) return false; u.pm = pm; u.pn = pn; return true; }
;     __device__ __forceinline__ long arow(int p) const { return (long)p * BM; }
; #define PG8_STAGE(bufoff, gbase, voff) do { _Pragma("unroll") for (int _i = 0; _i < 2; ++_i) \
;         __builtin_amdgcn_global_load_lds((const unsigned*)((const char*)(gbase) + (voff)[_i]), (PG8_LAS unsigned*)(lds + (bufoff) + ldsw + _i * 8192), 16, 0, 0); } while (0)
; #define PG8_LDA(dst, b, h) do { _Pragma("unroll") for (int m = 0; m < 4; ++m) _Pragma("unroll") for (int k = 0; k < 2; ++k) dst[m][k] = *(const PG8_LAS bf16x8*)(lds + PG8_SA(b, h) + aoff + m * 2048 + k * 1024); } while (0)
; template <class Epi, class Sched, bool ALIGN_EPI = false, bool SP2 = false>
; __device__ __forceinline__ void gemm_phase(PG8_LAS unsigned char* lds, const Gemm g, const Sched& S, const Epi& E) {
;     ...
;         const bool has_next = S.next(ui + 1, nxt);
;         const char* nA = has_next ? (const char*)g.A + S.arow(nxt.pm) * rowb : cA; const char* nB = has_next ? (const char*)g.Bt + (size_t)nxt.pn * tstep : cB;
;         for (int t = 0; t < nt; t += 2) {
;             const bool last = (t == nt - 2);
;             const char* a1 = cA + (size_t)(t + 1) * kstep;
;             const char* a2 = last ? nA : cA + (size_t)(t + 2) * kstep; const char* b2 = last ? nB : cB + (size_t)(t + 2) * kstep;
;             const char* a3 = a2 + kstep; const char* b3 = b2 + kstep;
;             if (last && has_next) S.a_ready(nxt);
;             if constexpr (SP2) {
;             PG8_LDB(B0, 0, 0); PG8_LDB(B1, 0, 1); PG8_SCHED; PG8_LDA(At, 0, 0); PG8_STAGE(PG8_SA(1, 1), a1 + hstep, voffA);
;             PG8_WAIT_V(8); PG8_WAIT_L(0); PG8_BAR; PG8_MMA(0, 0, At, B0); PG8_MMA(0, 1, At, B1); PG8_BAR; PG8_SCHED;
;             PG8_LDA(At, 0, 1); PG8_STAGE(PG8_SB(0, 0), b2, voffB); PG8_STAGE(PG8_SB(0, 1), b2 + hstep, voffB); PG8_STAGE(PG8_SA(0, 0), a2, voffA);
;             PG8_WAIT_V(8); PG8_WAIT_L(0); PG8_BAR; PG8_MMA(1, 0, At, B0); PG8_MMA(1, 1, At, B1); PG8_BAR; PG8_SCHED;
.LBB0_989:
	s_add_u32 s11, s14, 0x100
	s_addc_u32 s41, s15, 0
	s_mov_b32 s42, -2
	s_waitcnt vmcnt(0)
	s_add_u32 s14, s12, 0x100
	s_addc_u32 s15, s13, 0
	s_add_i32 s43, 0, 0x10000
	s_cmp_eq_u32 s42, 40
	s_cselect_b32 s19, s1, s15
	s_cselect_b32 s18, s0, s14
	v_add_u32_e32 v38, s43, v168
	s_cselect_b32 s17, s9, s41
	s_cselect_b32 s16, s8, s11
	s_add_i32 s44, 0, 0x14000
	ds_read_b128 v[138:141], v38
	ds_read_b128 v[162:165], v38 offset:1024
	ds_read_b128 v[172:175], v38 offset:2048
	ds_read_b128 v[176:179], v38 offset:3072
	v_add_u32_e32 v38, s44, v168
	ds_read_b128 v[186:189], v38
	ds_read_b128 v[190:193], v38 offset:1024
	ds_read_b128 v[194:197], v38 offset:2048
	ds_read_b128 v[198:201], v38 offset:3072
	v_lshl_add_u64 v[166:167], s[12:13], 0, v[158:159]
	s_add_i32 m0, s27, 0xc000
	ds_read_b128 v[208:211], v170
	ds_read_b128 v[218:221], v170 offset:1024
	ds_read_b128 v[226:229], v170 offset:2048
	ds_read_b128 v[230:233], v170 offset:3072
	ds_read_b128 v[234:237], v170 offset:4096
	ds_read_b128 v[238:241], v170 offset:5120
	ds_read_b128 v[242:245], v170 offset:6144
	ds_read_b128 v[246:249], v170 offset:7168
	global_load_lds_dwordx4 v[166:167], off
	v_lshl_add_u64 v[166:167], s[12:13], 0, v[160:161]
	s_add_i32 m0, s27, 0xe000
	s_nop 0
	global_load_lds_dwordx4 v[166:167], off
	s_waitcnt vmcnt(8)
	s_waitcnt lgkmcnt(0)
	s_barrier
	s_setprio 1
	s_waitcnt lgkmcnt(0)
	v_mfma_f32_16x16x32_bf16 v[134:137], v[138:141], v[208:211], 0
	v_mfma_f32_16x16x32_bf16 v[106:109], v[172:175], v[208:211], 0
	v_mfma_f32_16x16x32_bf16 v[130:133], v[138:141], v[226:229], 0
	v_mfma_f32_16x16x32_bf16 v[102:105], v[172:175], v[226:229], 0
	v_mfma_f32_16x16x32_bf16 v[126:129], v[138:141], v[234:237], 0
	v_mfma_f32_16x16x32_bf16 v[98:101], v[172:175], v[234:237], 0
	v_mfma_f32_16x16x32_bf16 v[122:125], v[138:141], v[242:245], 0
	v_mfma_f32_16x16x32_bf16 v[90:93], v[172:175], v[242:245], 0
	v_mfma_f32_16x16x32_bf16 v[134:137], v[162:165], v[218:221], v[134:137]
	v_mfma_f32_16x16x32_bf16 v[106:109], v[176:179], v[218:221], v[106:109]
	v_mfma_f32_16x16x32_bf16 v[130:133], v[162:165], v[230:233], v[130:133]
	v_mfma_f32_16x16x32_bf16 v[102:105], v[176:179], v[230:233], v[102:105]
	v_mfma_f32_16x16x32_bf16 v[126:129], v[162:165], v[238:241], v[126:129]
	v_mfma_f32_16x16x32_bf16 v[98:101], v[176:179], v[238:241], v[98:101]
	v_mfma_f32_16x16x32_bf16 v[122:125], v[162:165], v[246:249], v[122:125]
	v_mfma_f32_16x16x32_bf16 v[90:93], v[176:179], v[246:249], v[90:93]
	s_setprio 0
	s_setprio 1
	v_mfma_f32_16x16x32_bf16 v[82:85], v[186:189], v[208:211], 0
	v_mfma_f32_16x16x32_bf16 v[54:57], v[194:197], v[208:211], 0
	v_mfma_f32_16x16x32_bf16 v[74:77], v[186:189], v[226:229], 0
	v_mfma_f32_16x16x32_bf16 v[46:49], v[194:197], v[226:229], 0
	v_mfma_f32_16x16x32_bf16 v[66:69], v[186:189], v[234:237], 0
	v_mfma_f32_16x16x32_bf16 v[30:33], v[194:197], v[234:237], 0
	v_mfma_f32_16x16x32_bf16 v[58:61], v[186:189], v[242:245], 0
	v_mfma_f32_16x16x32_bf16 v[22:25], v[194:197], v[242:245], 0
	v_mfma_f32_16x16x32_bf16 v[82:85], v[190:193], v[218:221], v[82:85]
	v_mfma_f32_16x16x32_bf16 v[54:57], v[198:201], v[218:221], v[54:57]
	v_mfma_f32_16x16x32_bf16 v[74:77], v[190:193], v[230:233], v[74:77]
	v_mfma_f32_16x16x32_bf16 v[46:49], v[198:201], v[230:233], v[46:49]
	v_mfma_f32_16x16x32_bf16 v[66:69], v[190:193], v[238:241], v[66:69]
	v_mfma_f32_16x16x32_bf16 v[30:33], v[198:201], v[238:241], v[30:33]
	v_mfma_f32_16x16x32_bf16 v[58:61], v[190:193], v[246:249], v[58:61]
	v_mfma_f32_16x16x32_bf16 v[22:25], v[198:201], v[246:249], v[22:25]
	s_setprio 0
	s_barrier
	s_add_i32 s12, s43, s26
	v_lshl_add_u64 v[166:167], s[16:17], 0, v[34:35]
	s_mov_b32 m0, s12
	ds_read_b128 v[208:211], v170 offset:16384
	ds_read_b128 v[218:221], v170 offset:17408
	ds_read_b128 v[226:229], v170 offset:18432
	ds_read_b128 v[230:233], v170 offset:19456
	ds_read_b128 v[234:237], v170 offset:20480
	ds_read_b128 v[238:241], v170 offset:21504
	ds_read_b128 v[242:245], v170 offset:22528
	ds_read_b128 v[246:249], v170 offset:23552
	global_load_lds_dwordx4 v[166:167], off
	s_add_i32 m0, s12, 0x2000
	s_add_u32 s12, s16, 0xb0000
	v_lshl_add_u64 v[180:181], s[16:17], 0, v[36:37]
	s_addc_u32 s13, s17, 0
	s_add_i32 s43, s44, s26
	global_load_lds_dwordx4 v[180:181], off
	v_lshl_add_u64 v[202:203], s[12:13], 0, v[34:35]
	s_mov_b32 m0, s43
	v_lshl_add_u64 v[212:213], s[18:19], 0, v[36:37]
	global_load_lds_dwordx4 v[202:203], off
	v_lshl_add_u64 v[202:203], s[12:13], 0, v[36:37]
	s_add_i32 m0, s43, 0x2000
	s_nop 0
	global_load_lds_dwordx4 v[202:203], off
	v_lshl_add_u64 v[202:203], s[18:19], 0, v[34:35]
	s_mov_b32 m0, s27
	s_nop 0
	global_load_lds_dwordx4 v[202:203], off
	s_mov_b32 m0, s28
	s_nop 0
	global_load_lds_dwordx4 v[212:213], off
	s_waitcnt vmcnt(8)
	s_waitcnt lgkmcnt(0)
	s_barrier
; #define PG8_STAGE(bufoff, gbase, voff) do { _Pragma("unroll") for (int _i = 0; _i < 2; ++_i) \
;         __builtin_amdgcn_global_load_lds((const unsigned*)((const char*)(gbase) + (voff)[_i]), (PG8_LAS unsigned*)(lds + (bufoff) + ldsw + _i * 8192), 16, 0, 0); } while (0)
; #define PG8_LDA(dst, b, h) do { _Pragma("unroll") for (int m = 0; m < 4; ++m) _Pragma("unroll") for (int k = 0; k < 2; ++k) dst[m][k] = *(const PG8_LAS bf16x8*)(lds + PG8_SA(b, h) + aoff + m * 2048 + k * 1024); } while (0)
; #define PG8_LDB(dst, b, h) do { _Pragma("unroll") for (int n = 0; n < 2; ++n) _Pragma("unroll") for (int k = 0; k < 2; ++k) dst[n][k] = *(const PG8_LAS bf16x8*)(lds + PG8_SB(b, h) + boff + n * 2048 + k * 1024); } while (0)
; #define PG8_MMA(ai, bj, At, Bt) do { __builtin_amdgcn_s_setprio(1); _Pragma("unroll") for (int m = 0; m < 4; ++m) _Pragma("unroll") for (int n = 0; n < 2; ++n) _Pragma("unroll") for (int k = 0; k < 2; ++k) \
;         acc[ai][bj][m][n] = __builtin_amdgcn_mfma_f32_16x16x32_bf16(Bt[n][k], At[m][k], acc[ai][bj][m][n], 0, 0, 0); __builtin_amdgcn_s_setprio(0); } while (0)
; #define PG8_WAIT_V(n) asm volatile("s_waitcnt vmcnt(" #n ")" ::: "memory")
; #define PG8_WAIT_L(n) asm volatile("s_waitcnt lgkmcnt(" #n ")" ::: "memory")
; #define PG8_BAR __builtin_amdgcn_s_barrier()
; #define PG8_SCHED __builtin_amdgcn_sched_barrier(0)
; template <class Epi, class Sched, bool ALIGN_EPI = false, bool SP2 = false>
; __device__ __forceinline__ void gemm_phase(PG8_LAS unsigned char* lds, const Gemm g, const Sched& S, const Epi& E) {
;     ...
;             PG8_WAIT_V(8); PG8_WAIT_L(0); PG8_BAR; PG8_MMA(1, 0, At, B0); PG8_MMA(1, 1, At, B1); PG8_BAR; PG8_SCHED;
;             PG8_LDB(B0, 1, 0); PG8_LDB(B1, 1, 1); PG8_SCHED; PG8_LDA(At, 1, 0); PG8_STAGE(PG8_SA(0, 1), a2 + hstep, voffA);
;             PG8_WAIT_V(8); PG8_WAIT_L(0); PG8_BAR; PG8_MMA(0, 0, At, B0); PG8_MMA(0, 1, At, B1); PG8_BAR; PG8_SCHED;
	s_setprio 1
	s_waitcnt lgkmcnt(0)
	v_mfma_f32_16x16x32_bf16 v[118:121], v[138:141], v[208:211], 0
	v_mfma_f32_16x16x32_bf16 v[86:89], v[172:175], v[208:211], 0
	v_mfma_f32_16x16x32_bf16 v[114:117], v[138:141], v[226:229], 0
	v_mfma_f32_16x16x32_bf16 v[78:81], v[172:175], v[226:229], 0
	v_mfma_f32_16x16x32_bf16 v[110:113], v[138:141], v[234:237], 0
	v_mfma_f32_16x16x32_bf16 v[70:73], v[172:175], v[234:237], 0
	v_mfma_f32_16x16x32_bf16 v[94:97], v[138:141], v[242:245], 0
	v_mfma_f32_16x16x32_bf16 v[62:65], v[172:175], v[242:245], 0
	v_mfma_f32_16x16x32_bf16 v[118:121], v[162:165], v[218:221], v[118:121]
	v_mfma_f32_16x16x32_bf16 v[86:89], v[176:179], v[218:221], v[86:89]
	v_mfma_f32_16x16x32_bf16 v[114:117], v[162:165], v[230:233], v[114:117]
	v_mfma_f32_16x16x32_bf16 v[78:81], v[176:179], v[230:233], v[78:81]
	v_mfma_f32_16x16x32_bf16 v[110:113], v[162:165], v[238:241], v[110:113]
	v_mfma_f32_16x16x32_bf16 v[70:73], v[176:179], v[238:241], v[70:73]
	v_mfma_f32_16x16x32_bf16 v[94:97], v[162:165], v[246:249], v[94:97]
	v_mfma_f32_16x16x32_bf16 v[62:65], v[176:179], v[246:249], v[62:65]
	s_setprio 0
	s_setprio 1
	v_mfma_f32_16x16x32_bf16 v[50:53], v[186:189], v[208:211], 0
	v_mfma_f32_16x16x32_bf16 v[14:17], v[194:197], v[208:211], 0
	v_mfma_f32_16x16x32_bf16 v[42:45], v[186:189], v[226:229], 0
	v_mfma_f32_16x16x32_bf16 v[10:13], v[194:197], v[226:229], 0
	v_mfma_f32_16x16x32_bf16 v[26:29], v[186:189], v[234:237], 0
	v_mfma_f32_16x16x32_bf16 v[6:9], v[194:197], v[234:237], 0
	v_mfma_f32_16x16x32_bf16 v[18:21], v[186:189], v[242:245], 0
	v_mfma_f32_16x16x32_bf16 v[2:5], v[194:197], v[242:245], 0
	v_mfma_f32_16x16x32_bf16 v[50:53], v[190:193], v[218:221], v[50:53]
	v_mfma_f32_16x16x32_bf16 v[14:17], v[198:201], v[218:221], v[14:17]
	v_mfma_f32_16x16x32_bf16 v[42:45], v[190:193], v[230:233], v[42:45]
	v_mfma_f32_16x16x32_bf16 v[10:13], v[198:201], v[230:233], v[10:13]
	v_mfma_f32_16x16x32_bf16 v[26:29], v[190:193], v[238:241], v[26:29]
	v_mfma_f32_16x16x32_bf16 v[6:9], v[198:201], v[238:241], v[6:9]
	v_mfma_f32_16x16x32_bf16 v[18:21], v[190:193], v[246:249], v[18:21]
	v_mfma_f32_16x16x32_bf16 v[2:5], v[198:201], v[246:249], v[2:5]
	s_setprio 0
	s_barrier
	s_add_i32 s43, 0, 0x18000
	v_add_u32_e32 v38, s43, v168
	s_add_i32 s44, 0, 0x1c000
	ds_read_b128 v[138:141], v38
	ds_read_b128 v[162:165], v38 offset:1024
	ds_read_b128 v[172:175], v38 offset:2048
	ds_read_b128 v[176:179], v38 offset:3072
	v_add_u32_e32 v38, s44, v168
	ds_read_b128 v[186:189], v38
	ds_read_b128 v[190:193], v38 offset:1024
	ds_read_b128 v[194:197], v38 offset:2048
	ds_read_b128 v[198:201], v38 offset:3072
	s_add_u32 s12, s18, 0xb0000
	s_addc_u32 s13, s19, 0
	s_mov_b32 m0, s29
	v_lshl_add_u64 v[250:251], s[12:13], 0, v[34:35]
	ds_read_b128 v[208:211], v170 offset:32768
	ds_read_b128 v[218:221], v170 offset:33792
	ds_read_b128 v[226:229], v170 offset:34816
	ds_read_b128 v[230:233], v170 offset:35840
	ds_read_b128 v[234:237], v170 offset:36864
	ds_read_b128 v[238:241], v170 offset:37888
	ds_read_b128 v[242:245], v170 offset:38912
	ds_read_b128 v[246:249], v170 offset:39936
	global_load_lds_dwordx4 v[250:251], off
	v_lshl_add_u64 v[250:251], s[12:13], 0, v[36:37]
	s_mov_b32 m0, s30
	s_nop 0
	global_load_lds_dwordx4 v[250:251], off
	s_waitcnt vmcnt(8)
	s_waitcnt lgkmcnt(0)
	s_barrier
	s_setprio 1
	s_waitcnt lgkmcnt(0)
	v_mfma_f32_16x16x32_bf16 v[134:137], v[138:141], v[208:211], v[134:137]
	v_mfma_f32_16x16x32_bf16 v[106:109], v[172:175], v[208:211], v[106:109]
	v_mfma_f32_16x16x32_bf16 v[130:133], v[138:141], v[226:229], v[130:133]
	v_mfma_f32_16x16x32_bf16 v[102:105], v[172:175], v[226:229], v[102:105]
	v_mfma_f32_16x16x32_bf16 v[126:129], v[138:141], v[234:237], v[126:129]
	v_mfma_f32_16x16x32_bf16 v[98:101], v[172:175], v[234:237], v[98:101]
	v_mfma_f32_16x16x32_bf16 v[122:125], v[138:141], v[242:245], v[122:125]
	v_mfma_f32_16x16x32_bf16 v[90:93], v[172:175], v[242:245], v[90:93]
	v_mfma_f32_16x16x32_bf16 v[134:137], v[162:165], v[218:221], v[134:137]
	v_mfma_f32_16x16x32_bf16 v[106:109], v[176:179], v[218:221], v[106:109]
	v_mfma_f32_16x16x32_bf16 v[130:133], v[162:165], v[230:233], v[130:133]
	v_mfma_f32_16x16x32_bf16 v[102:105], v[176:179], v[230:233], v[102:105]
	v_mfma_f32_16x16x32_bf16 v[126:129], v[162:165], v[238:241], v[126:129]
	v_mfma_f32_16x16x32_bf16 v[98:101], v[176:179], v[238:241], v[98:101]
	v_mfma_f32_16x16x32_bf16 v[122:125], v[162:165], v[246:249], v[122:125]
	v_mfma_f32_16x16x32_bf16 v[90:93], v[176:179], v[246:249], v[90:93]
	s_setprio 0
	s_setprio 1
	v_mfma_f32_16x16x32_bf16 v[82:85], v[186:189], v[208:211], v[82:85]
	v_mfma_f32_16x16x32_bf16 v[54:57], v[194:197], v[208:211], v[54:57]
	v_mfma_f32_16x16x32_bf16 v[74:77], v[186:189], v[226:229], v[74:77]
	v_mfma_f32_16x16x32_bf16 v[46:49], v[194:197], v[226:229], v[46:49]
	v_mfma_f32_16x16x32_bf16 v[66:69], v[186:189], v[234:237], v[66:69]
	v_mfma_f32_16x16x32_bf16 v[30:33], v[194:197], v[234:237], v[30:33]
	v_mfma_f32_16x16x32_bf16 v[58:61], v[186:189], v[242:245], v[58:61]
	v_mfma_f32_16x16x32_bf16 v[22:25], v[194:197], v[242:245], v[22:25]
	v_mfma_f32_16x16x32_bf16 v[82:85], v[190:193], v[218:221], v[82:85]
	v_mfma_f32_16x16x32_bf16 v[54:57], v[198:201], v[218:221], v[54:57]
	v_mfma_f32_16x16x32_bf16 v[74:77], v[190:193], v[230:233], v[74:77]
	v_mfma_f32_16x16x32_bf16 v[46:49], v[198:201], v[230:233], v[46:49]
	v_mfma_f32_16x16x32_bf16 v[66:69], v[190:193], v[238:241], v[66:69]
	v_mfma_f32_16x16x32_bf16 v[30:33], v[198:201], v[238:241], v[30:33]
	v_mfma_f32_16x16x32_bf16 v[58:61], v[190:193], v[246:249], v[58:61]
	v_mfma_f32_16x16x32_bf16 v[22:25], v[198:201], v[246:249], v[22:25]
	s_setprio 0
	s_barrier
; #define PG8_STAGE(bufoff, gbase, voff) do { _Pragma("unroll") for (int _i = 0; _i < 2; ++_i) \
;         __builtin_amdgcn_global_load_lds((const unsigned*)((const char*)(gbase) + (voff)[_i]), (PG8_LAS unsigned*)(lds + (bufoff) + ldsw + _i * 8192), 16, 0, 0); } while (0)
; #define PG8_LDA(dst, b, h) do { _Pragma("unroll") for (int m = 0; m < 4; ++m) _Pragma("unroll") for (int k = 0; k < 2; ++k) dst[m][k] = *(const PG8_LAS bf16x8*)(lds + PG8_SA(b, h) + aoff + m * 2048 + k * 1024); } while (0)
; #define PG8_LDB(dst, b, h) do { _Pragma("unroll") for (int n = 0; n < 2; ++n) _Pragma("unroll") for (int k = 0; k < 2; ++k) dst[n][k] = *(const PG8_LAS bf16x8*)(lds + PG8_SB(b, h) + boff + n * 2048 + k * 1024); } while (0)
; #define PG8_MMA(ai, bj, At, Bt) do { __builtin_amdgcn_s_setprio(1); _Pragma("unroll") for (int m = 0; m < 4; ++m) _Pragma("unroll") for (int n = 0; n < 2; ++n) _Pragma("unroll") for (int k = 0; k < 2; ++k) \
;         acc[ai][bj][m][n] = __builtin_amdgcn_mfma_f32_16x16x32_bf16(Bt[n][k], At[m][k], acc[ai][bj][m][n], 0, 0, 0); __builtin_amdgcn_s_setprio(0); } while (0)
; #define PG8_WAIT_V(n) asm volatile("s_waitcnt vmcnt(" #n ")" ::: "memory")
; #define PG8_WAIT_L(n) asm volatile("s_waitcnt lgkmcnt(" #n ")" ::: "memory")
; #define PG8_BAR __builtin_amdgcn_s_barrier()
; #define PG8_SCHED __builtin_amdgcn_sched_barrier(0)
; template <class Epi, class Sched, bool ALIGN_EPI = false, bool SP2 = false>
; __device__ __forceinline__ void gemm_phase(PG8_LAS unsigned char* lds, const Gemm g, const Sched& S, const Epi& E) {
;     ...
;         for (int t = 0; t < nt; t += 2) {
;     ...
;             PG8_LDB(B0, 1, 0); PG8_LDB(B1, 1, 1); PG8_SCHED; PG8_LDA(At, 1, 0); PG8_STAGE(PG8_SA(0, 1), a2 + hstep, voffA);
;             PG8_WAIT_V(8); PG8_WAIT_L(0); PG8_BAR; PG8_MMA(0, 0, At, B0); PG8_MMA(0, 1, At, B1); PG8_BAR; PG8_SCHED;
;             PG8_LDA(At, 1, 1); PG8_STAGE(PG8_SB(1, 0), b3, voffB); PG8_STAGE(PG8_SB(1, 1), b3 + hstep, voffB); PG8_STAGE(PG8_SA(1, 0), a3, voffA);
;             PG8_WAIT_V(8); PG8_WAIT_L(0); PG8_BAR; PG8_MMA(1, 0, At, B0); PG8_MMA(1, 1, At, B1); PG8_BAR; PG8_SCHED;
	s_add_i32 s12, s43, s26
	v_lshl_add_u64 v[166:167], v[166:167], 0, s[70:71]
	s_mov_b32 m0, s12
	ds_read_b128 v[208:211], v170 offset:49152
	ds_read_b128 v[218:221], v170 offset:50176
	ds_read_b128 v[226:229], v170 offset:51200
	ds_read_b128 v[230:233], v170 offset:52224
	ds_read_b128 v[234:237], v170 offset:53248
	ds_read_b128 v[238:241], v170 offset:54272
	ds_read_b128 v[242:245], v170 offset:55296
	ds_read_b128 v[246:249], v170 offset:56320
	global_load_lds_dwordx4 v[166:167], off
	s_add_i32 m0, s12, 0x2000
	s_add_u32 s12, s16, 0xb0080
	v_lshl_add_u64 v[166:167], v[180:181], 0, s[70:71]
	s_addc_u32 s13, s17, 0
	s_add_i32 s16, s44, s26
	global_load_lds_dwordx4 v[166:167], off
	v_lshl_add_u64 v[166:167], s[12:13], 0, v[34:35]
	s_mov_b32 m0, s16
	s_nop 0
	global_load_lds_dwordx4 v[166:167], off
	v_lshl_add_u64 v[166:167], s[12:13], 0, v[36:37]
	s_add_i32 m0, s16, 0x2000
	s_nop 0
	global_load_lds_dwordx4 v[166:167], off
	v_lshl_add_u64 v[166:167], v[202:203], 0, s[70:71]
	s_mov_b32 m0, s35
	s_nop 0
	global_load_lds_dwordx4 v[166:167], off
	v_lshl_add_u64 v[166:167], v[212:213], 0, s[70:71]
	s_mov_b32 m0, s36
	s_nop 0
	global_load_lds_dwordx4 v[166:167], off
	s_waitcnt vmcnt(8)
	s_waitcnt lgkmcnt(0)
	s_barrier
	s_setprio 1
	s_waitcnt lgkmcnt(0)
	v_mfma_f32_16x16x32_bf16 v[118:121], v[138:141], v[208:211], v[118:121]
	v_mfma_f32_16x16x32_bf16 v[86:89], v[172:175], v[208:211], v[86:89]
	v_mfma_f32_16x16x32_bf16 v[114:117], v[138:141], v[226:229], v[114:117]
	v_mfma_f32_16x16x32_bf16 v[78:81], v[172:175], v[226:229], v[78:81]
	v_mfma_f32_16x16x32_bf16 v[110:113], v[138:141], v[234:237], v[110:113]
	v_mfma_f32_16x16x32_bf16 v[70:73], v[172:175], v[234:237], v[70:73]
	v_mfma_f32_16x16x32_bf16 v[94:97], v[138:141], v[242:245], v[94:97]
	v_mfma_f32_16x16x32_bf16 v[62:65], v[172:175], v[242:245], v[62:65]
	v_mfma_f32_16x16x32_bf16 v[118:121], v[162:165], v[218:221], v[118:121]
	v_mfma_f32_16x16x32_bf16 v[86:89], v[176:179], v[218:221], v[86:89]
	v_mfma_f32_16x16x32_bf16 v[114:117], v[162:165], v[230:233], v[114:117]
	v_mfma_f32_16x16x32_bf16 v[78:81], v[176:179], v[230:233], v[78:81]
	v_mfma_f32_16x16x32_bf16 v[110:113], v[162:165], v[238:241], v[110:113]
	v_mfma_f32_16x16x32_bf16 v[70:73], v[176:179], v[238:241], v[70:73]
	v_mfma_f32_16x16x32_bf16 v[94:97], v[162:165], v[246:249], v[94:97]
	v_mfma_f32_16x16x32_bf16 v[62:65], v[176:179], v[246:249], v[62:65]
	s_setprio 0
	s_setprio 1
	v_mfma_f32_16x16x32_bf16 v[50:53], v[186:189], v[208:211], v[50:53]
	v_mfma_f32_16x16x32_bf16 v[14:17], v[194:197], v[208:211], v[14:17]
	v_mfma_f32_16x16x32_bf16 v[42:45], v[186:189], v[226:229], v[42:45]
	v_mfma_f32_16x16x32_bf16 v[10:13], v[194:197], v[226:229], v[10:13]
	v_mfma_f32_16x16x32_bf16 v[26:29], v[186:189], v[234:237], v[26:29]
	v_mfma_f32_16x16x32_bf16 v[6:9], v[194:197], v[234:237], v[6:9]
	v_mfma_f32_16x16x32_bf16 v[18:21], v[186:189], v[242:245], v[18:21]
	v_mfma_f32_16x16x32_bf16 v[2:5], v[194:197], v[242:245], v[2:5]
	v_mfma_f32_16x16x32_bf16 v[50:53], v[190:193], v[218:221], v[50:53]
	v_mfma_f32_16x16x32_bf16 v[14:17], v[198:201], v[218:221], v[14:17]
	v_mfma_f32_16x16x32_bf16 v[42:45], v[190:193], v[230:233], v[42:45]
	v_mfma_f32_16x16x32_bf16 v[10:13], v[198:201], v[230:233], v[10:13]
	v_mfma_f32_16x16x32_bf16 v[26:29], v[190:193], v[238:241], v[26:29]
	v_mfma_f32_16x16x32_bf16 v[6:9], v[198:201], v[238:241], v[6:9]
	v_mfma_f32_16x16x32_bf16 v[18:21], v[190:193], v[246:249], v[18:21]
	v_mfma_f32_16x16x32_bf16 v[2:5], v[198:201], v[246:249], v[2:5]
	s_setprio 0
	s_barrier
	s_add_i32 s42, s42, 2
	s_add_u32 s11, s11, 0x100
	s_addc_u32 s41, s41, 0
	s_cmp_gt_u32 s42, 41
	s_mov_b64 s[12:13], s[14:15]
	.p2align 3

;     __device__ __forceinline__ long arow(int pm) const { return (long)pm * BM; }
;     __device__ __forceinline__ long arow(int pm) const { if (pm < 132) { const int b = pm / 33, i = pm - b * 33; return (long)b * 8192 + 254 * i - 1; } return 32768 + (long)(pm - 132) * 256; }
;     __device__ __forceinline__ long arow(int p) const { return (long)p * BM; }
; #define PG8_WAIT_V(n) asm volatile("s_waitcnt vmcnt(" #n ")" ::: "memory")
; #define PG8_BAR __builtin_amdgcn_s_barrier()
; template <class Epi, class Sched, bool ALIGN_EPI = false, bool SP2 = false>
; __device__ __forceinline__ void gemm_phase(PG8_LAS unsigned char* lds, const Gemm g, const Sched& S, const Epi& E) {
;     ...
;     for (int i = 0; i < 2; ++i) { int R, C; stage_rc(tid * 16 + i * 8192, R, C); const int Rb = Epi::PERM ? ((R & ~31) + perm32(R & 31)) : R;
;         voffA[i] = (unsigned)(R * LD + C) * 2u; voffB[i] = (unsigned)(Rb * LD + C) * 2u; }
;     ...
;     f32x4 acc[2][2][4][2];
; #pragma unroll
;     for (int a = 0; a < 2; ++a)
; #pragma unroll
;         for (int b = 0; b < 2; ++b)
; #pragma unroll
;             for (int m = 0; m < 4; ++m)
; #pragma unroll
;                 for (int n = 0; n < 2; ++n) acc[a][b][m][n] = (f32x4){0.f, 0.f, 0.f, 0.f};
;     bf16x8 At[4][2], B0[2][2], B1[2][2];
;     const long rowb = (long)LD * 2;
;     const char* cA = (const char*)g.A + S.arow(cur.pm) * rowb; const char* cB = (const char*)g.Bt + (size_t)cur.pn * tstep;
;     S.a_ready(cur);
;     if constexpr (SP2) {
;         PG8_STAGE(PG8_SB(0, 0), cB, voffB); PG8_STAGE(PG8_SB(0, 1), cB + hstep, voffB); PG8_STAGE(PG8_SA(0, 0), cA, voffA); PG8_STAGE(PG8_SA(0, 1), cA + hstep, voffA);
;         if (wr == 1) PG8_BAR;
;         PG8_WAIT_V(2); PG8_BAR;
;         PG8_STAGE(PG8_SB(1, 0), cB + kstep, voffB); PG8_STAGE(PG8_SA(1, 0), cA + kstep, voffA); PG8_STAGE(PG8_SB(1, 1), cB + hstep + kstep, voffB);
;         PG8_WAIT_V(6); PG8_BAR;
;     } else {
;         PG8_STAGE(PG8_SB(0, 0), cB, voffB); PG8_STAGE(PG8_SA(0, 0), cA, voffA); PG8_STAGE(PG8_SB(0, 1), cB + hstep, voffB); PG8_STAGE(PG8_SA(0, 1), cA + hstep, voffA);
;         if (wr == 1) PG8_BAR;
;         PG8_WAIT_V(4); PG8_BAR;
;         PG8_STAGE(PG8_SB(1, 0), cB + kstep, voffB); PG8_STAGE(PG8_SA(1, 0), cA + kstep, voffA); PG8_STAGE(PG8_SB(1, 1), cB + hstep + kstep, voffB);
;         PG8_WAIT_V(6); PG8_BAR;
;     }
.LBB0_1009:
	v_bfe_u32 v143, v18, 4, 2
	s_lshl_b32 s6, s6, 5
	v_and_b32_e32 v19, 15, v18
	v_lshlrev_b32_e32 v20, 4, v143
	v_lshlrev_b32_e32 v18, 2, v18
	s_and_b32 s18, s6, 0x60
	s_add_i32 m0, s14, 0x18000
	v_lshl_add_u64 v[8:9], v[8:9], 0, s[70:71]
	v_lshl_or_b32 v142, s4, 6, v19
	v_lshl_or_b32 v19, v19, 6, v20
	v_and_b32_e32 v18, 32, v18
	s_lshl_b32 s4, s4, 13
	s_lshl_b32 s6, s18, 7
	s_waitcnt vmcnt(2)
	s_barrier
	global_load_lds_dwordx4 v[8:9], off
	v_lshl_add_u64 v[6:7], v[6:7], 0, s[70:71]
	s_add_i32 m0, s14, 0x1a000
	s_add_i32 s19, s14, 0x8000
	s_add_i32 s20, s14, 0xa000
	v_bitop3_b32 v144, v19, s6, v18 bitop3:0xde
	global_load_lds_dwordx4 v[6:7], off
	v_lshl_add_u64 v[4:5], v[4:5], 0, s[70:71]
	s_mov_b32 m0, s19
	s_add_u32 s6, s0, 0xb0080
	global_load_lds_dwordx4 v[4:5], off
	v_lshl_add_u64 v[2:3], v[2:3], 0, s[70:71]
	s_mov_b32 m0, s20
	s_addc_u32 s7, s1, 0
	global_load_lds_dwordx4 v[2:3], off
	s_add_i32 m0, s14, 0x1c000
	v_lshl_add_u64 v[2:3], s[6:7], 0, v[34:35]
	global_load_lds_dwordx4 v[2:3], off
	v_lshl_add_u64 v[2:3], s[6:7], 0, v[36:37]
	s_add_i32 m0, s14, 0x1e000
	s_movk_i32 s8, 0xb00
	global_load_lds_dwordx4 v[2:3], off
	v_lshrrev_b32_e32 v3, 1, v10
	v_mul_lo_u32 v2, v12, s8
	s_mov_b32 s9, 0xb000
	v_bitop3_b32 v18, v19, s4, v18 bitop3:0xde
	v_mad_u64_u32 v[2:3], s[6:7], v3, s9, v[2:3]
	v_readlane_b32 s4, v254, 20
	v_or_b32_e32 v2, v2, v11
	s_add_u32 s4, s4, s5
	v_readlane_b32 s5, v254, 21
	v_add_lshl_u32 v2, v2, v14, 1
	v_mov_b32_e32 v3, v35
	s_addc_u32 s5, s5, 0
	v_lshl_add_u64 v[138:139], s[4:5], 0, v[2:3]
	v_lshrrev_b32_e32 v3, 1, v13
	v_mul_lo_u32 v2, v16, s8
	v_mad_u64_u32 v[2:3], s[6:7], v3, s9, v[2:3]
	v_or_b32_e32 v2, v2, v15
	s_waitcnt vmcnt(6)
	v_add_lshl_u32 v2, v2, v17, 1
	v_mov_b32_e32 v3, v35
	v_lshl_add_u64 v[140:141], s[4:5], 0, v[2:3]
	v_mov_b32_e32 v2, 0
	s_mov_b32 s8, 0
	s_mov_b64 s[4:5], 0
	v_add_u32_e32 v145, 0, v18
	v_mov_b32_e32 v3, v2
	v_mov_b32_e32 v4, v2
	v_mov_b32_e32 v5, v2
	v_mov_b32_e32 v42, v2
	v_mov_b32_e32 v43, v2
	v_mov_b32_e32 v44, v2
	v_mov_b32_e32 v45, v2
	v_mov_b32_e32 v6, v2
	v_mov_b32_e32 v7, v2
	v_mov_b32_e32 v8, v2
	v_mov_b32_e32 v9, v2
	v_mov_b32_e32 v46, v2
	v_mov_b32_e32 v47, v2
	v_mov_b32_e32 v48, v2
	v_mov_b32_e32 v49, v2
	v_mov_b32_e32 v10, v2
	v_mov_b32_e32 v11, v2
	v_mov_b32_e32 v12, v2
	v_mov_b32_e32 v13, v2
	v_mov_b32_e32 v50, v2
	v_mov_b32_e32 v51, v2
	v_mov_b32_e32 v52, v2
	v_mov_b32_e32 v53, v2
	v_mov_b32_e32 v14, v2
	v_mov_b32_e32 v15, v2
	v_mov_b32_e32 v16, v2
	v_mov_b32_e32 v17, v2
	v_mov_b32_e32 v54, v2
	v_mov_b32_e32 v55, v2
	v_mov_b32_e32 v56, v2
	v_mov_b32_e32 v57, v2
	v_mov_b32_e32 v74, v2
	v_mov_b32_e32 v75, v2
	v_mov_b32_e32 v76, v2
	v_mov_b32_e32 v77, v2
	v_mov_b32_e32 v106, v2
	v_mov_b32_e32 v107, v2
	v_mov_b32_e32 v108, v2
	v_mov_b32_e32 v109, v2
	v_mov_b32_e32 v78, v2
	v_mov_b32_e32 v79, v2
	v_mov_b32_e32 v80, v2
	v_mov_b32_e32 v81, v2
	v_mov_b32_e32 v110, v2
	v_mov_b32_e32 v111, v2
	v_mov_b32_e32 v112, v2
	v_mov_b32_e32 v113, v2
	v_mov_b32_e32 v82, v2
	v_mov_b32_e32 v83, v2
	v_mov_b32_e32 v84, v2
	v_mov_b32_e32 v85, v2
	v_mov_b32_e32 v114, v2
	v_mov_b32_e32 v115, v2
	v_mov_b32_e32 v116, v2
	v_mov_b32_e32 v117, v2
	v_mov_b32_e32 v86, v2
	v_mov_b32_e32 v87, v2
	v_mov_b32_e32 v88, v2
	v_mov_b32_e32 v89, v2
	v_mov_b32_e32 v118, v2
	v_mov_b32_e32 v119, v2
	v_mov_b32_e32 v120, v2
	v_mov_b32_e32 v121, v2
	v_mov_b32_e32 v18, v2
	v_mov_b32_e32 v19, v2
	v_mov_b32_e32 v20, v2
	v_mov_b32_e32 v21, v2
	v_mov_b32_e32 v58, v2
	v_mov_b32_e32 v59, v2
	v_mov_b32_e32 v60, v2
	v_mov_b32_e32 v61, v2
	v_mov_b32_e32 v22, v2
	v_mov_b32_e32 v23, v2
	v_mov_b32_e32 v24, v2
	v_mov_b32_e32 v25, v2
	v_mov_b32_e32 v62, v2
	v_mov_b32_e32 v63, v2
	v_mov_b32_e32 v64, v2
	v_mov_b32_e32 v65, v2
	v_mov_b32_e32 v26, v2
	v_mov_b32_e32 v27, v2
	v_mov_b32_e32 v28, v2
	v_mov_b32_e32 v29, v2
	v_mov_b32_e32 v66, v2
	v_mov_b32_e32 v67, v2
	v_mov_b32_e32 v68, v2
	v_mov_b32_e32 v69, v2
	v_mov_b32_e32 v30, v2
	v_mov_b32_e32 v31, v2
	s_waitcnt vmcnt(0)
	v_mov_b32_e32 v32, v2
	v_mov_b32_e32 v33, v2
	v_mov_b32_e32 v70, v2
	v_mov_b32_e32 v71, v2
	v_mov_b32_e32 v72, v2
	v_mov_b32_e32 v73, v2
	v_mov_b32_e32 v90, v2
	v_mov_b32_e32 v91, v2
	v_mov_b32_e32 v92, v2
	v_mov_b32_e32 v93, v2
	v_mov_b32_e32 v122, v2
	v_mov_b32_e32 v123, v2
	v_mov_b32_e32 v124, v2
	v_mov_b32_e32 v125, v2
	v_mov_b32_e32 v94, v2
	v_mov_b32_e32 v95, v2
	v_mov_b32_e32 v96, v2
	v_mov_b32_e32 v97, v2
	v_mov_b32_e32 v126, v2
	v_mov_b32_e32 v127, v2
	v_mov_b32_e32 v128, v2
	v_mov_b32_e32 v129, v2
	v_mov_b32_e32 v98, v2
	v_mov_b32_e32 v99, v2
	v_mov_b32_e32 v100, v2
	v_mov_b32_e32 v101, v2
	v_mov_b32_e32 v130, v2
	v_mov_b32_e32 v131, v2
	v_mov_b32_e32 v132, v2
	v_mov_b32_e32 v133, v2
	v_mov_b32_e32 v102, v2
	v_mov_b32_e32 v103, v2
	v_mov_b32_e32 v104, v2
	v_mov_b32_e32 v105, v2
	v_mov_b32_e32 v134, v2
	v_mov_b32_e32 v135, v2
	v_mov_b32_e32 v136, v2
	v_mov_b32_e32 v137, v2
	s_barrier
	.p2align 3
